# residual epilogues: row sum-of-squares cross-lane reduction via v_permlane16/32_swap instead of ds_bpermute round trips
# speedup vs baseline: 1.0067x; 1.0067x over previous
.LBB0_223:
	v_mov_b32_e32 v110, v218
	s_lshl_b32 s24, s55, 8
	s_add_i32 s24, s24, s45
	v_and_b32_e32 v196, 15, v110
	v_bfe_u32 v197, v110, 4, 2
	v_or_b32_e32 v212, s24, v196
	s_lshl_b32 s24, s54, 8
	v_lshl_or_b32 v110, v197, 3, s24
	v_ashrrev_i32_e32 v213, 31, v212
	v_or_b32_e32 v110, s46, v110
	v_lshlrev_b64 v[112:113], 11, v[212:213]
	v_lshl_add_u64 v[112:113], s[16:17], 0, v[112:113]
	v_ashrrev_i32_e32 v111, 31, v110
	v_lshl_add_u64 v[210:211], v[110:111], 1, v[112:113]
	global_load_dwordx4 v[228:231], v[210:211], off
	global_load_dwordx4 v[186:189], v[210:211], off offset:256
	v_add_co_u32_e32 v110, vcc, s75, v210
	s_mov_b32 s24, 0x58000
	s_nop 0
	v_addc_co_u32_e32 v111, vcc, 0, v211, vcc
	global_load_dwordx4 v[182:185], v[110:111], off
	global_load_dwordx4 v[178:181], v[110:111], off offset:256
	v_add_co_u32_e32 v110, vcc, s71, v210
	v_lshlrev_b32_e32 v198, 6, v197
	s_nop 0
	v_addc_co_u32_e32 v111, vcc, 0, v211, vcc
	global_load_dwordx4 v[174:177], v[110:111], off
	global_load_dwordx4 v[170:173], v[110:111], off offset:256
	v_add_co_u32_e32 v110, vcc, s74, v210
	v_lshlrev_b32_e32 v196, 2, v196
	s_nop 0
	v_addc_co_u32_e32 v111, vcc, 0, v211, vcc
	global_load_dwordx4 v[166:169], v[110:111], off
	global_load_dwordx4 v[162:165], v[110:111], off offset:256
	v_add_co_u32_e32 v110, vcc, s87, v210
	v_bitop3_b32 v216, v198, 64, v196 bitop3:0x36
	s_nop 0
	v_addc_co_u32_e32 v111, vcc, 0, v211, vcc
	global_load_dwordx4 v[154:157], v[110:111], off
	global_load_dwordx4 v[146:149], v[110:111], off offset:256
	v_add_co_u32_e32 v110, vcc, s92, v210
	v_bitop3_b32 v215, v198, s82, v196 bitop3:0x36
	s_nop 0
	v_addc_co_u32_e32 v111, vcc, 0, v211, vcc
	global_load_dwordx4 v[142:145], v[110:111], off
	global_load_dwordx4 v[138:141], v[110:111], off offset:256
	v_add_co_u32_e32 v110, vcc, s93, v210
	s_waitcnt vmcnt(0)
	v_lshlrev_b32_e32 v232, 16, v228
	v_addc_co_u32_e32 v111, vcc, 0, v211, vcc
	global_load_dwordx4 v[134:137], v[110:111], off
	global_load_dwordx4 v[122:125], v[110:111], off offset:256
	v_add_co_u32_e32 v110, vcc, s24, v210
	v_and_b32_e32 v233, 0xffff0000, v228
	s_nop 0
	v_addc_co_u32_e32 v111, vcc, 0, v211, vcc
	global_load_dwordx4 v[118:121], v[110:111], off
	s_nop 0
	global_load_dwordx4 v[110:113], v[110:111], off offset:256
	v_lshlrev_b32_e32 v228, 16, v229
	v_and_b32_e32 v229, 0xffff0000, v229
	v_pk_fma_f32 v[158:159], v[158:159], 0.5, v[232:233] op_sel_hi:[1,0,1]
	v_pk_fma_f32 v[160:161], v[160:161], 0.5, v[228:229] op_sel_hi:[1,0,1]
	v_cvt_pk_bf16_f32 v158, v158, v159
	v_cvt_pk_bf16_f32 v159, v160, v161
	v_lshlrev_b32_e32 v160, 16, v230
	v_and_b32_e32 v161, 0xffff0000, v230
	v_pk_fma_f32 v[150:151], v[150:151], 0.5, v[160:161] op_sel_hi:[1,0,1]
	v_cmp_eq_u32_e32 vcc, 0, v197
	v_cvt_pk_bf16_f32 v160, v150, v151
	v_lshlrev_b32_e32 v150, 16, v231
	v_and_b32_e32 v151, 0xffff0000, v231
	v_pk_fma_f32 v[150:151], v[152:153], 0.5, v[150:151] op_sel_hi:[1,0,1]
	s_nop 0
	v_cvt_pk_bf16_f32 v161, v150, v151
	v_and_b32_e32 v151, 0xffff0000, v158
	v_lshlrev_b32_e32 v150, 16, v158
	v_mul_f32_e32 v152, v151, v151
	v_fmac_f32_e32 v152, v150, v150
	v_lshlrev_b32_e32 v150, 16, v159
	v_fmac_f32_e32 v152, v150, v150
	v_and_b32_e32 v150, 0xffff0000, v159
	v_fmac_f32_e32 v152, v150, v150
	v_lshlrev_b32_e32 v150, 16, v160
	v_fmac_f32_e32 v152, v150, v150
	v_and_b32_e32 v150, 0xffff0000, v160
	v_fmac_f32_e32 v152, v150, v150
	v_lshlrev_b32_e32 v150, 16, v161
	v_fmac_f32_e32 v152, v150, v150
	v_and_b32_e32 v150, 0xffff0000, v161
	v_fmac_f32_e32 v152, v150, v150
	v_lshlrev_b32_e32 v150, 16, v186
	v_and_b32_e32 v151, 0xffff0000, v186
	v_pk_fma_f32 v[130:131], v[130:131], 0.5, v[150:151] op_sel_hi:[1,0,1]
	v_lshlrev_b32_e32 v150, 16, v187
	v_and_b32_e32 v151, 0xffff0000, v187
	v_pk_fma_f32 v[132:133], v[132:133], 0.5, v[150:151] op_sel_hi:[1,0,1]
	v_cvt_pk_bf16_f32 v130, v130, v131
	v_cvt_pk_bf16_f32 v131, v132, v133
	v_lshlrev_b32_e32 v132, 16, v188
	v_and_b32_e32 v133, 0xffff0000, v188
	v_pk_fma_f32 v[126:127], v[126:127], 0.5, v[132:133] op_sel_hi:[1,0,1]
	global_store_dwordx4 v[210:211], v[158:161], off
	v_cvt_pk_bf16_f32 v132, v126, v127
	v_lshlrev_b32_e32 v126, 16, v189
	v_and_b32_e32 v127, 0xffff0000, v189
	v_pk_fma_f32 v[126:127], v[128:129], 0.5, v[126:127] op_sel_hi:[1,0,1]
	s_nop 0
	v_cvt_pk_bf16_f32 v133, v126, v127
	v_and_b32_e32 v127, 0xffff0000, v130
	v_lshlrev_b32_e32 v126, 16, v130
	v_mul_f32_e32 v127, v127, v127
	v_fmac_f32_e32 v127, v126, v126
	v_lshlrev_b32_e32 v126, 16, v131
	v_fmac_f32_e32 v127, v126, v126
	v_and_b32_e32 v126, 0xffff0000, v131
	v_fmac_f32_e32 v127, v126, v126
	v_lshlrev_b32_e32 v126, 16, v132
	v_fmac_f32_e32 v127, v126, v126
	v_and_b32_e32 v126, 0xffff0000, v132
	v_fmac_f32_e32 v127, v126, v126
	v_lshlrev_b32_e32 v126, 16, v133
	v_fmac_f32_e32 v127, v126, v126
	v_and_b32_e32 v126, 0xffff0000, v133
	v_fmac_f32_e32 v127, v126, v126
	v_add_f32_e32 v126, v152, v127
	v_mov_b32_e32 v127, v126
	s_nop 1
	v_permlane16_swap_b32_e32 v127, v126
	global_store_dwordx4 v[210:211], v[130:133], off offset:256
	s_waitcnt lgkmcnt(0)
	v_add_f32_e32 v128, v126, v127
	v_mov_b32_e32 v129, v128
	s_nop 1
	v_permlane32_swap_b32_e32 v129, v128
	v_lshl_add_u64 v[126:127], v[212:213], 3, s[18:19]
	s_and_saveexec_b64 s[24:25], vcc
	s_cbranch_execz .LBB0_225
	s_waitcnt lgkmcnt(0)
	v_add_f32_e32 v128, v128, v129
	v_mul_f32_e32 v128, 0x48800000, v128
	v_cvt_u32_f32_e32 v128, v128
	v_mov_b32_e32 v129, v0
	global_atomic_add_x2 v[126:127], v[128:129], off
.LBB0_225:
	s_or_b64 exec, exec, s[24:25]
	v_lshlrev_b32_e32 v128, 16, v182
	s_waitcnt lgkmcnt(0)
	v_and_b32_e32 v129, 0xffff0000, v182
	v_pk_fma_f32 v[114:115], v[114:115], 0.5, v[128:129] op_sel_hi:[1,0,1]
	v_lshlrev_b32_e32 v128, 16, v183
	v_and_b32_e32 v129, 0xffff0000, v183
	v_pk_fma_f32 v[116:117], v[116:117], 0.5, v[128:129] op_sel_hi:[1,0,1]
	v_cvt_pk_bf16_f32 v114, v114, v115
	v_cvt_pk_bf16_f32 v115, v116, v117
	v_lshlrev_b32_e32 v116, 16, v184
	v_and_b32_e32 v117, 0xffff0000, v184
	v_pk_fma_f32 v[106:107], v[106:107], 0.5, v[116:117] op_sel_hi:[1,0,1]
	s_mov_b64 s[24:25], 0x8000
	v_cvt_pk_bf16_f32 v116, v106, v107
	v_lshlrev_b32_e32 v106, 16, v185
	v_and_b32_e32 v107, 0xffff0000, v185
	v_pk_fma_f32 v[106:107], v[108:109], 0.5, v[106:107] op_sel_hi:[1,0,1]
	s_nop 0
	v_cvt_pk_bf16_f32 v117, v106, v107
	v_and_b32_e32 v107, 0xffff0000, v114
	v_lshlrev_b32_e32 v106, 16, v114
	v_mul_f32_e32 v108, v107, v107
	v_fmac_f32_e32 v108, v106, v106
	v_lshlrev_b32_e32 v106, 16, v115
	v_fmac_f32_e32 v108, v106, v106
	v_and_b32_e32 v106, 0xffff0000, v115
	v_fmac_f32_e32 v108, v106, v106
	v_lshlrev_b32_e32 v106, 16, v116
	v_fmac_f32_e32 v108, v106, v106
	v_and_b32_e32 v106, 0xffff0000, v116
	v_fmac_f32_e32 v108, v106, v106
	v_lshlrev_b32_e32 v106, 16, v117
	v_fmac_f32_e32 v108, v106, v106
	v_and_b32_e32 v106, 0xffff0000, v117
	v_fmac_f32_e32 v108, v106, v106
	v_lshlrev_b32_e32 v106, 16, v178
	v_and_b32_e32 v107, 0xffff0000, v178
	v_pk_fma_f32 v[102:103], v[102:103], 0.5, v[106:107] op_sel_hi:[1,0,1]
	v_lshlrev_b32_e32 v106, 16, v179
	v_and_b32_e32 v107, 0xffff0000, v179
	v_pk_fma_f32 v[104:105], v[104:105], 0.5, v[106:107] op_sel_hi:[1,0,1]
	v_cvt_pk_bf16_f32 v102, v102, v103
	v_cvt_pk_bf16_f32 v103, v104, v105
	v_lshlrev_b32_e32 v104, 16, v180
	v_and_b32_e32 v105, 0xffff0000, v180
	v_pk_fma_f32 v[98:99], v[98:99], 0.5, v[104:105] op_sel_hi:[1,0,1]
	s_nop 0
	v_cvt_pk_bf16_f32 v104, v98, v99
	v_lshlrev_b32_e32 v98, 16, v181
	v_and_b32_e32 v99, 0xffff0000, v181
	v_pk_fma_f32 v[98:99], v[100:101], 0.5, v[98:99] op_sel_hi:[1,0,1]
	v_lshl_add_u64 v[100:101], v[210:211], 0, s[24:25]
	v_cvt_pk_bf16_f32 v105, v98, v99
	v_and_b32_e32 v99, 0xffff0000, v102
	v_lshlrev_b32_e32 v98, 16, v102
	v_mul_f32_e32 v99, v99, v99
	v_fmac_f32_e32 v99, v98, v98
	v_lshlrev_b32_e32 v98, 16, v103
	v_fmac_f32_e32 v99, v98, v98
	v_and_b32_e32 v98, 0xffff0000, v103
	v_fmac_f32_e32 v99, v98, v98
	v_lshlrev_b32_e32 v98, 16, v104
	v_fmac_f32_e32 v99, v98, v98
	v_and_b32_e32 v98, 0xffff0000, v104
	v_fmac_f32_e32 v99, v98, v98
	v_lshlrev_b32_e32 v98, 16, v105
	v_fmac_f32_e32 v99, v98, v98
	v_and_b32_e32 v98, 0xffff0000, v105
	v_fmac_f32_e32 v99, v98, v98
	v_add_f32_e32 v98, v108, v99
	v_mov_b32_e32 v99, v98
	s_nop 1
	v_permlane16_swap_b32_e32 v99, v98
	s_mov_b64 s[24:25], 0x8100
	v_lshl_add_u64 v[106:107], v[210:211], 0, s[24:25]
	global_store_dwordx4 v[100:101], v[114:117], off
	global_store_dwordx4 v[106:107], v[102:105], off
	s_waitcnt lgkmcnt(0)
	v_add_f32_e32 v98, v98, v99
	v_mov_b32_e32 v99, v98
	s_nop 1
	v_permlane32_swap_b32_e32 v99, v98
	s_and_saveexec_b64 s[24:25], vcc
	s_cbranch_execz .LBB0_227
	s_waitcnt lgkmcnt(0)
	v_add_f32_e32 v98, v98, v99
	v_mul_f32_e32 v98, 0x48800000, v98
	v_cvt_u32_f32_e32 v98, v98
	v_mov_b32_e32 v99, v0
	global_atomic_add_x2 v[126:127], v[98:99], off offset:128
.LBB0_227:
	s_or_b64 exec, exec, s[24:25]
	v_lshlrev_b32_e32 v98, 16, v174
	s_waitcnt lgkmcnt(0)
	v_and_b32_e32 v99, 0xffff0000, v174
	v_pk_fma_f32 v[94:95], v[94:95], 0.5, v[98:99] op_sel_hi:[1,0,1]
	v_lshlrev_b32_e32 v98, 16, v175
	v_and_b32_e32 v99, 0xffff0000, v175
	v_pk_fma_f32 v[96:97], v[96:97], 0.5, v[98:99] op_sel_hi:[1,0,1]
	v_cvt_pk_bf16_f32 v94, v94, v95
	v_cvt_pk_bf16_f32 v95, v96, v97
	v_lshlrev_b32_e32 v96, 16, v176
	v_and_b32_e32 v97, 0xffff0000, v176
	v_pk_fma_f32 v[90:91], v[90:91], 0.5, v[96:97] op_sel_hi:[1,0,1]
	s_mov_b64 s[24:25], 0x10100
	v_cvt_pk_bf16_f32 v96, v90, v91
	v_lshlrev_b32_e32 v90, 16, v177
	v_and_b32_e32 v91, 0xffff0000, v177
	v_pk_fma_f32 v[90:91], v[92:93], 0.5, v[90:91] op_sel_hi:[1,0,1]
	s_nop 0
	v_cvt_pk_bf16_f32 v97, v90, v91
	v_and_b32_e32 v91, 0xffff0000, v94
	v_lshlrev_b32_e32 v90, 16, v94
	v_mul_f32_e32 v92, v91, v91
	v_fmac_f32_e32 v92, v90, v90
	v_lshlrev_b32_e32 v90, 16, v95
	v_fmac_f32_e32 v92, v90, v90
	v_and_b32_e32 v90, 0xffff0000, v95
	v_fmac_f32_e32 v92, v90, v90
	v_lshlrev_b32_e32 v90, 16, v96
	v_fmac_f32_e32 v92, v90, v90
	v_and_b32_e32 v90, 0xffff0000, v96
	v_fmac_f32_e32 v92, v90, v90
	v_lshlrev_b32_e32 v90, 16, v97
	v_fmac_f32_e32 v92, v90, v90
	v_and_b32_e32 v90, 0xffff0000, v97
	v_fmac_f32_e32 v92, v90, v90
	v_lshlrev_b32_e32 v90, 16, v170
	v_and_b32_e32 v91, 0xffff0000, v170
	v_pk_fma_f32 v[86:87], v[86:87], 0.5, v[90:91] op_sel_hi:[1,0,1]
	v_lshlrev_b32_e32 v90, 16, v171
	v_and_b32_e32 v91, 0xffff0000, v171
	v_pk_fma_f32 v[88:89], v[88:89], 0.5, v[90:91] op_sel_hi:[1,0,1]
	v_cvt_pk_bf16_f32 v86, v86, v87
	v_cvt_pk_bf16_f32 v87, v88, v89
	v_lshlrev_b32_e32 v88, 16, v172
	v_and_b32_e32 v89, 0xffff0000, v172
	v_pk_fma_f32 v[82:83], v[82:83], 0.5, v[88:89] op_sel_hi:[1,0,1]
	v_lshl_add_u64 v[90:91], v[210:211], 0, s[24:25]
	v_cvt_pk_bf16_f32 v88, v82, v83
	v_lshlrev_b32_e32 v82, 16, v173
	v_and_b32_e32 v83, 0xffff0000, v173
	v_pk_fma_f32 v[82:83], v[84:85], 0.5, v[82:83] op_sel_hi:[1,0,1]
	v_lshl_add_u64 v[84:85], v[210:211], 0, s[90:91]
	v_cvt_pk_bf16_f32 v89, v82, v83
	v_and_b32_e32 v83, 0xffff0000, v86
	v_lshlrev_b32_e32 v82, 16, v86
	v_mul_f32_e32 v83, v83, v83
	v_fmac_f32_e32 v83, v82, v82
	v_lshlrev_b32_e32 v82, 16, v87
	v_fmac_f32_e32 v83, v82, v82
	v_and_b32_e32 v82, 0xffff0000, v87
	v_fmac_f32_e32 v83, v82, v82
	v_lshlrev_b32_e32 v82, 16, v88
	v_fmac_f32_e32 v83, v82, v82
	v_and_b32_e32 v82, 0xffff0000, v88
	v_fmac_f32_e32 v83, v82, v82
	v_lshlrev_b32_e32 v82, 16, v89
	v_fmac_f32_e32 v83, v82, v82
	v_and_b32_e32 v82, 0xffff0000, v89
	v_fmac_f32_e32 v83, v82, v82
	v_add_f32_e32 v82, v92, v83
	v_mov_b32_e32 v83, v82
	s_nop 1
	v_permlane16_swap_b32_e32 v83, v82
	global_store_dwordx4 v[84:85], v[94:97], off
	global_store_dwordx4 v[90:91], v[86:89], off
	s_waitcnt lgkmcnt(0)
	v_add_f32_e32 v82, v82, v83
	v_mov_b32_e32 v83, v82
	s_nop 1
	v_permlane32_swap_b32_e32 v83, v82
	s_and_saveexec_b64 s[24:25], vcc
	s_cbranch_execz .LBB0_229
	s_waitcnt lgkmcnt(0)
	v_add_f32_e32 v82, v82, v83
	v_mul_f32_e32 v82, 0x48800000, v82
	v_cvt_u32_f32_e32 v82, v82
	v_mov_b32_e32 v83, v0
	global_atomic_add_x2 v[126:127], v[82:83], off offset:256
.LBB0_229:
	s_or_b64 exec, exec, s[24:25]
	v_lshlrev_b32_e32 v82, 16, v166
	s_waitcnt lgkmcnt(0)
	v_and_b32_e32 v83, 0xffff0000, v166
	v_pk_fma_f32 v[78:79], v[78:79], 0.5, v[82:83] op_sel_hi:[1,0,1]
	v_lshlrev_b32_e32 v82, 16, v167
	v_and_b32_e32 v83, 0xffff0000, v167
	v_pk_fma_f32 v[80:81], v[80:81], 0.5, v[82:83] op_sel_hi:[1,0,1]
	v_cvt_pk_bf16_f32 v78, v78, v79
	v_cvt_pk_bf16_f32 v79, v80, v81
	v_lshlrev_b32_e32 v80, 16, v168
	v_and_b32_e32 v81, 0xffff0000, v168
	v_pk_fma_f32 v[74:75], v[74:75], 0.5, v[80:81] op_sel_hi:[1,0,1]
	s_mov_b64 s[24:25], 0x18000
	v_cvt_pk_bf16_f32 v80, v74, v75
	v_lshlrev_b32_e32 v74, 16, v169
	v_and_b32_e32 v75, 0xffff0000, v169
	v_pk_fma_f32 v[74:75], v[76:77], 0.5, v[74:75] op_sel_hi:[1,0,1]
	s_nop 0
	v_cvt_pk_bf16_f32 v81, v74, v75
	v_and_b32_e32 v75, 0xffff0000, v78
	v_lshlrev_b32_e32 v74, 16, v78
	v_mul_f32_e32 v76, v75, v75
	v_fmac_f32_e32 v76, v74, v74
	v_lshlrev_b32_e32 v74, 16, v79
	v_fmac_f32_e32 v76, v74, v74
	v_and_b32_e32 v74, 0xffff0000, v79
	v_fmac_f32_e32 v76, v74, v74
	v_lshlrev_b32_e32 v74, 16, v80
	v_fmac_f32_e32 v76, v74, v74
	v_and_b32_e32 v74, 0xffff0000, v80
	v_fmac_f32_e32 v76, v74, v74
	v_lshlrev_b32_e32 v74, 16, v81
	v_fmac_f32_e32 v76, v74, v74
	v_and_b32_e32 v74, 0xffff0000, v81
	v_fmac_f32_e32 v76, v74, v74
	v_lshlrev_b32_e32 v74, 16, v162
	v_and_b32_e32 v75, 0xffff0000, v162
	v_pk_fma_f32 v[70:71], v[70:71], 0.5, v[74:75] op_sel_hi:[1,0,1]
	v_lshlrev_b32_e32 v74, 16, v163
	v_and_b32_e32 v75, 0xffff0000, v163
	v_pk_fma_f32 v[72:73], v[72:73], 0.5, v[74:75] op_sel_hi:[1,0,1]
	v_cvt_pk_bf16_f32 v70, v70, v71
	v_cvt_pk_bf16_f32 v71, v72, v73
	v_lshlrev_b32_e32 v72, 16, v164
	v_and_b32_e32 v73, 0xffff0000, v164
	v_pk_fma_f32 v[66:67], v[66:67], 0.5, v[72:73] op_sel_hi:[1,0,1]
	s_nop 0
	v_cvt_pk_bf16_f32 v72, v66, v67
	v_lshlrev_b32_e32 v66, 16, v165
	v_and_b32_e32 v67, 0xffff0000, v165
	v_pk_fma_f32 v[66:67], v[68:69], 0.5, v[66:67] op_sel_hi:[1,0,1]
	v_lshl_add_u64 v[68:69], v[210:211], 0, s[24:25]
	v_cvt_pk_bf16_f32 v73, v66, v67
	v_and_b32_e32 v67, 0xffff0000, v70
	v_lshlrev_b32_e32 v66, 16, v70
	v_mul_f32_e32 v67, v67, v67
	v_fmac_f32_e32 v67, v66, v66
	v_lshlrev_b32_e32 v66, 16, v71
	v_fmac_f32_e32 v67, v66, v66
	v_and_b32_e32 v66, 0xffff0000, v71
	v_fmac_f32_e32 v67, v66, v66
	v_lshlrev_b32_e32 v66, 16, v72
	v_fmac_f32_e32 v67, v66, v66
	v_and_b32_e32 v66, 0xffff0000, v72
	v_fmac_f32_e32 v67, v66, v66
	v_lshlrev_b32_e32 v66, 16, v73
	v_fmac_f32_e32 v67, v66, v66
	v_and_b32_e32 v66, 0xffff0000, v73
	v_fmac_f32_e32 v67, v66, v66
	v_add_f32_e32 v66, v76, v67
	v_mov_b32_e32 v67, v66
	s_nop 1
	v_permlane16_swap_b32_e32 v67, v66
	s_mov_b64 s[24:25], 0x18100
	v_lshl_add_u64 v[74:75], v[210:211], 0, s[24:25]
	global_store_dwordx4 v[68:69], v[78:81], off
	global_store_dwordx4 v[74:75], v[70:73], off
	s_waitcnt lgkmcnt(0)
	v_add_f32_e32 v66, v66, v67
	v_mov_b32_e32 v67, v66
	s_nop 1
	v_permlane32_swap_b32_e32 v67, v66
	s_and_saveexec_b64 s[24:25], vcc
	s_cbranch_execz .LBB0_231
	s_waitcnt lgkmcnt(0)
	v_add_f32_e32 v66, v66, v67
	v_mul_f32_e32 v66, 0x48800000, v66
	v_cvt_u32_f32_e32 v66, v66
	v_mov_b32_e32 v67, v0
	global_atomic_add_x2 v[126:127], v[66:67], off offset:384
.LBB0_231:
	s_or_b64 exec, exec, s[24:25]
	v_lshlrev_b32_e32 v66, 16, v154
	s_waitcnt lgkmcnt(0)
	v_and_b32_e32 v67, 0xffff0000, v154
	v_pk_fma_f32 v[62:63], v[62:63], 0.5, v[66:67] op_sel_hi:[1,0,1]
	v_lshlrev_b32_e32 v66, 16, v155
	v_and_b32_e32 v67, 0xffff0000, v155
	v_pk_fma_f32 v[64:65], v[64:65], 0.5, v[66:67] op_sel_hi:[1,0,1]
	v_cvt_pk_bf16_f32 v62, v62, v63
	v_cvt_pk_bf16_f32 v63, v64, v65
	v_lshlrev_b32_e32 v64, 16, v156
	v_and_b32_e32 v65, 0xffff0000, v156
	v_pk_fma_f32 v[58:59], v[58:59], 0.5, v[64:65] op_sel_hi:[1,0,1]
	s_mov_b64 s[24:25], 0x40100
	v_cvt_pk_bf16_f32 v64, v58, v59
	v_lshlrev_b32_e32 v58, 16, v157
	v_and_b32_e32 v59, 0xffff0000, v157
	v_pk_fma_f32 v[58:59], v[60:61], 0.5, v[58:59] op_sel_hi:[1,0,1]
	s_nop 0
	v_cvt_pk_bf16_f32 v65, v58, v59
	v_and_b32_e32 v59, 0xffff0000, v62
	v_lshlrev_b32_e32 v58, 16, v62
	v_mul_f32_e32 v60, v59, v59
	v_fmac_f32_e32 v60, v58, v58
	v_lshlrev_b32_e32 v58, 16, v63
	v_fmac_f32_e32 v60, v58, v58
	v_and_b32_e32 v58, 0xffff0000, v63
	v_fmac_f32_e32 v60, v58, v58
	v_lshlrev_b32_e32 v58, 16, v64
	v_fmac_f32_e32 v60, v58, v58
	v_and_b32_e32 v58, 0xffff0000, v64
	v_fmac_f32_e32 v60, v58, v58
	v_lshlrev_b32_e32 v58, 16, v65
	v_fmac_f32_e32 v60, v58, v58
	v_and_b32_e32 v58, 0xffff0000, v65
	v_fmac_f32_e32 v60, v58, v58
	v_lshlrev_b32_e32 v58, 16, v146
	v_and_b32_e32 v59, 0xffff0000, v146
	v_pk_fma_f32 v[54:55], v[54:55], 0.5, v[58:59] op_sel_hi:[1,0,1]
	v_lshlrev_b32_e32 v58, 16, v147
	v_and_b32_e32 v59, 0xffff0000, v147
	v_pk_fma_f32 v[56:57], v[56:57], 0.5, v[58:59] op_sel_hi:[1,0,1]
	v_cvt_pk_bf16_f32 v54, v54, v55
	v_cvt_pk_bf16_f32 v55, v56, v57
	v_lshlrev_b32_e32 v56, 16, v148
	v_and_b32_e32 v57, 0xffff0000, v148
	v_pk_fma_f32 v[50:51], v[50:51], 0.5, v[56:57] op_sel_hi:[1,0,1]
	v_lshl_add_u64 v[58:59], v[210:211], 0, s[24:25]
	v_cvt_pk_bf16_f32 v56, v50, v51
	v_lshlrev_b32_e32 v50, 16, v149
	v_and_b32_e32 v51, 0xffff0000, v149
	v_pk_fma_f32 v[50:51], v[52:53], 0.5, v[50:51] op_sel_hi:[1,0,1]
	v_lshl_add_u64 v[52:53], v[210:211], 0, s[72:73]
	v_cvt_pk_bf16_f32 v57, v50, v51
	v_and_b32_e32 v51, 0xffff0000, v54
	v_lshlrev_b32_e32 v50, 16, v54
	v_mul_f32_e32 v51, v51, v51
	v_fmac_f32_e32 v51, v50, v50
	v_lshlrev_b32_e32 v50, 16, v55
	v_fmac_f32_e32 v51, v50, v50
	v_and_b32_e32 v50, 0xffff0000, v55
	v_fmac_f32_e32 v51, v50, v50
	v_lshlrev_b32_e32 v50, 16, v56
	v_fmac_f32_e32 v51, v50, v50
	v_and_b32_e32 v50, 0xffff0000, v56
	v_fmac_f32_e32 v51, v50, v50
	v_lshlrev_b32_e32 v50, 16, v57
	v_fmac_f32_e32 v51, v50, v50
	v_and_b32_e32 v50, 0xffff0000, v57
	v_fmac_f32_e32 v51, v50, v50
	v_add_f32_e32 v50, v60, v51
	v_mov_b32_e32 v51, v50
	s_nop 1
	v_permlane16_swap_b32_e32 v51, v50
	global_store_dwordx4 v[52:53], v[62:65], off
	global_store_dwordx4 v[58:59], v[54:57], off
	s_waitcnt lgkmcnt(0)
	v_add_f32_e32 v50, v50, v51
	v_mov_b32_e32 v51, v50
	s_nop 1
	v_permlane32_swap_b32_e32 v51, v50
	s_and_saveexec_b64 s[24:25], vcc
	s_cbranch_execz .LBB0_233
	s_waitcnt lgkmcnt(0)
	v_add_f32_e32 v50, v50, v51
	v_mul_f32_e32 v50, 0x48800000, v50
	v_cvt_u32_f32_e32 v50, v50
	v_mov_b32_e32 v51, v0
	global_atomic_add_x2 v[126:127], v[50:51], off offset:1024
.LBB0_233:
	s_or_b64 exec, exec, s[24:25]
	v_lshlrev_b32_e32 v50, 16, v142
	s_waitcnt lgkmcnt(0)
	v_and_b32_e32 v51, 0xffff0000, v142
	v_pk_fma_f32 v[46:47], v[46:47], 0.5, v[50:51] op_sel_hi:[1,0,1]
	v_lshlrev_b32_e32 v50, 16, v143
	v_and_b32_e32 v51, 0xffff0000, v143
	v_pk_fma_f32 v[48:49], v[48:49], 0.5, v[50:51] op_sel_hi:[1,0,1]
	v_cvt_pk_bf16_f32 v46, v46, v47
	v_cvt_pk_bf16_f32 v47, v48, v49
	v_lshlrev_b32_e32 v48, 16, v144
	v_and_b32_e32 v49, 0xffff0000, v144
	v_pk_fma_f32 v[42:43], v[42:43], 0.5, v[48:49] op_sel_hi:[1,0,1]
	s_mov_b64 s[24:25], 0x48000
	v_cvt_pk_bf16_f32 v48, v42, v43
	v_lshlrev_b32_e32 v42, 16, v145
	v_and_b32_e32 v43, 0xffff0000, v145
	v_pk_fma_f32 v[42:43], v[44:45], 0.5, v[42:43] op_sel_hi:[1,0,1]
	s_nop 0
	v_cvt_pk_bf16_f32 v49, v42, v43
	v_and_b32_e32 v43, 0xffff0000, v46
	v_lshlrev_b32_e32 v42, 16, v46
	v_mul_f32_e32 v44, v43, v43
	v_fmac_f32_e32 v44, v42, v42
	v_lshlrev_b32_e32 v42, 16, v47
	v_fmac_f32_e32 v44, v42, v42
	v_and_b32_e32 v42, 0xffff0000, v47
	v_fmac_f32_e32 v44, v42, v42
	v_lshlrev_b32_e32 v42, 16, v48
	v_fmac_f32_e32 v44, v42, v42
	v_and_b32_e32 v42, 0xffff0000, v48
	v_fmac_f32_e32 v44, v42, v42
	v_lshlrev_b32_e32 v42, 16, v49
	v_fmac_f32_e32 v44, v42, v42
	v_and_b32_e32 v42, 0xffff0000, v49
	v_fmac_f32_e32 v44, v42, v42
	v_lshlrev_b32_e32 v42, 16, v138
	v_and_b32_e32 v43, 0xffff0000, v138
	v_pk_fma_f32 v[38:39], v[38:39], 0.5, v[42:43] op_sel_hi:[1,0,1]
	v_lshlrev_b32_e32 v42, 16, v139
	v_and_b32_e32 v43, 0xffff0000, v139
	v_pk_fma_f32 v[40:41], v[40:41], 0.5, v[42:43] op_sel_hi:[1,0,1]
	v_cvt_pk_bf16_f32 v38, v38, v39
	v_cvt_pk_bf16_f32 v39, v40, v41
	v_lshlrev_b32_e32 v40, 16, v140
	v_and_b32_e32 v41, 0xffff0000, v140
	v_pk_fma_f32 v[34:35], v[34:35], 0.5, v[40:41] op_sel_hi:[1,0,1]
	s_nop 0
	v_cvt_pk_bf16_f32 v40, v34, v35
	v_lshlrev_b32_e32 v34, 16, v141
	v_and_b32_e32 v35, 0xffff0000, v141
	v_pk_fma_f32 v[34:35], v[36:37], 0.5, v[34:35] op_sel_hi:[1,0,1]
	v_lshl_add_u64 v[36:37], v[210:211], 0, s[24:25]
	v_cvt_pk_bf16_f32 v41, v34, v35
	v_and_b32_e32 v35, 0xffff0000, v38
	v_lshlrev_b32_e32 v34, 16, v38
	v_mul_f32_e32 v35, v35, v35
	v_fmac_f32_e32 v35, v34, v34
	v_lshlrev_b32_e32 v34, 16, v39
	v_fmac_f32_e32 v35, v34, v34
	v_and_b32_e32 v34, 0xffff0000, v39
	v_fmac_f32_e32 v35, v34, v34
	v_lshlrev_b32_e32 v34, 16, v40
	v_fmac_f32_e32 v35, v34, v34
	v_and_b32_e32 v34, 0xffff0000, v40
	v_fmac_f32_e32 v35, v34, v34
	v_lshlrev_b32_e32 v34, 16, v41
	v_fmac_f32_e32 v35, v34, v34
	v_and_b32_e32 v34, 0xffff0000, v41
	v_fmac_f32_e32 v35, v34, v34
	v_add_f32_e32 v34, v44, v35
	v_mov_b32_e32 v35, v34
	s_nop 1
	v_permlane16_swap_b32_e32 v35, v34
	s_mov_b64 s[24:25], 0x48100
	v_lshl_add_u64 v[42:43], v[210:211], 0, s[24:25]
	global_store_dwordx4 v[36:37], v[46:49], off
	global_store_dwordx4 v[42:43], v[38:41], off
	s_waitcnt lgkmcnt(0)
	v_add_f32_e32 v34, v34, v35
	v_mov_b32_e32 v35, v34
	s_nop 1
	v_permlane32_swap_b32_e32 v35, v34
	s_and_saveexec_b64 s[24:25], vcc
	s_cbranch_execz .LBB0_235
	s_waitcnt lgkmcnt(0)
	v_add_f32_e32 v34, v34, v35
	v_mul_f32_e32 v34, 0x48800000, v34
	v_cvt_u32_f32_e32 v34, v34
	v_mov_b32_e32 v35, v0
	global_atomic_add_x2 v[126:127], v[34:35], off offset:1152
.LBB0_235:
	s_or_b64 exec, exec, s[24:25]
	s_waitcnt vmcnt(15)
	v_lshlrev_b32_e32 v34, 16, v134
	s_waitcnt lgkmcnt(0)
	v_and_b32_e32 v35, 0xffff0000, v134
	v_pk_fma_f32 v[30:31], v[30:31], 0.5, v[34:35] op_sel_hi:[1,0,1]
	v_lshlrev_b32_e32 v34, 16, v135
	v_and_b32_e32 v35, 0xffff0000, v135
	v_pk_fma_f32 v[32:33], v[32:33], 0.5, v[34:35] op_sel_hi:[1,0,1]
	v_cvt_pk_bf16_f32 v30, v30, v31
	v_cvt_pk_bf16_f32 v31, v32, v33
	v_lshlrev_b32_e32 v32, 16, v136
	v_and_b32_e32 v33, 0xffff0000, v136
	v_pk_fma_f32 v[26:27], v[26:27], 0.5, v[32:33] op_sel_hi:[1,0,1]
	s_mov_b64 s[24:25], 0x50000
	v_cvt_pk_bf16_f32 v32, v26, v27
	v_lshlrev_b32_e32 v26, 16, v137
	v_and_b32_e32 v27, 0xffff0000, v137
	v_pk_fma_f32 v[26:27], v[28:29], 0.5, v[26:27] op_sel_hi:[1,0,1]
	s_nop 0
	v_cvt_pk_bf16_f32 v33, v26, v27
	v_and_b32_e32 v27, 0xffff0000, v30
	v_lshlrev_b32_e32 v26, 16, v30
	v_mul_f32_e32 v28, v27, v27
	v_fmac_f32_e32 v28, v26, v26
	v_lshlrev_b32_e32 v26, 16, v31
	v_fmac_f32_e32 v28, v26, v26
	v_and_b32_e32 v26, 0xffff0000, v31
	v_fmac_f32_e32 v28, v26, v26
	v_lshlrev_b32_e32 v26, 16, v32
	v_fmac_f32_e32 v28, v26, v26
	v_and_b32_e32 v26, 0xffff0000, v32
	v_fmac_f32_e32 v28, v26, v26
	v_lshlrev_b32_e32 v26, 16, v33
	v_fmac_f32_e32 v28, v26, v26
	v_and_b32_e32 v26, 0xffff0000, v33
	v_fmac_f32_e32 v28, v26, v26
	s_waitcnt vmcnt(14)
	v_lshlrev_b32_e32 v26, 16, v122
	v_and_b32_e32 v27, 0xffff0000, v122
	v_pk_fma_f32 v[22:23], v[22:23], 0.5, v[26:27] op_sel_hi:[1,0,1]
	v_lshlrev_b32_e32 v26, 16, v123
	v_and_b32_e32 v27, 0xffff0000, v123
	v_pk_fma_f32 v[24:25], v[24:25], 0.5, v[26:27] op_sel_hi:[1,0,1]
	v_cvt_pk_bf16_f32 v22, v22, v23
	v_cvt_pk_bf16_f32 v23, v24, v25
	v_lshlrev_b32_e32 v24, 16, v124
	v_and_b32_e32 v25, 0xffff0000, v124
	v_pk_fma_f32 v[18:19], v[18:19], 0.5, v[24:25] op_sel_hi:[1,0,1]
	s_nop 0
	v_cvt_pk_bf16_f32 v24, v18, v19
	v_lshlrev_b32_e32 v18, 16, v125
	v_and_b32_e32 v19, 0xffff0000, v125
	v_pk_fma_f32 v[18:19], v[20:21], 0.5, v[18:19] op_sel_hi:[1,0,1]
	v_lshl_add_u64 v[20:21], v[210:211], 0, s[24:25]
	v_cvt_pk_bf16_f32 v25, v18, v19
	v_and_b32_e32 v19, 0xffff0000, v22
	v_lshlrev_b32_e32 v18, 16, v22
	v_mul_f32_e32 v19, v19, v19
	v_fmac_f32_e32 v19, v18, v18
	v_lshlrev_b32_e32 v18, 16, v23
	v_fmac_f32_e32 v19, v18, v18
	v_and_b32_e32 v18, 0xffff0000, v23
	v_fmac_f32_e32 v19, v18, v18
	v_lshlrev_b32_e32 v18, 16, v24
	v_fmac_f32_e32 v19, v18, v18
	v_and_b32_e32 v18, 0xffff0000, v24
	v_fmac_f32_e32 v19, v18, v18
	v_lshlrev_b32_e32 v18, 16, v25
	v_fmac_f32_e32 v19, v18, v18
	v_and_b32_e32 v18, 0xffff0000, v25
	v_fmac_f32_e32 v19, v18, v18
	v_add_f32_e32 v18, v28, v19
	v_mov_b32_e32 v19, v18
	s_nop 1
	v_permlane16_swap_b32_e32 v19, v18
	s_mov_b64 s[24:25], 0x50100
	v_lshl_add_u64 v[26:27], v[210:211], 0, s[24:25]
	global_store_dwordx4 v[20:21], v[30:33], off
	global_store_dwordx4 v[26:27], v[22:25], off
	s_waitcnt lgkmcnt(0)
	v_add_f32_e32 v18, v18, v19
	v_mov_b32_e32 v19, v18
	s_nop 1
	v_permlane32_swap_b32_e32 v19, v18
	s_and_saveexec_b64 s[24:25], vcc
	s_cbranch_execz .LBB0_237
	s_waitcnt lgkmcnt(0)
	v_add_f32_e32 v18, v18, v19
	v_mul_f32_e32 v18, 0x48800000, v18
	v_cvt_u32_f32_e32 v18, v18
	v_mov_b32_e32 v19, v0
	global_atomic_add_x2 v[126:127], v[18:19], off offset:1280
.LBB0_237:
	s_or_b64 exec, exec, s[24:25]
	s_waitcnt vmcnt(15)
	v_lshlrev_b32_e32 v18, 16, v118
	s_waitcnt lgkmcnt(0)
	v_and_b32_e32 v19, 0xffff0000, v118
	v_pk_fma_f32 v[14:15], v[14:15], 0.5, v[18:19] op_sel_hi:[1,0,1]
	v_lshlrev_b32_e32 v18, 16, v119
	v_and_b32_e32 v19, 0xffff0000, v119
	v_pk_fma_f32 v[16:17], v[16:17], 0.5, v[18:19] op_sel_hi:[1,0,1]
	v_cvt_pk_bf16_f32 v14, v14, v15
	v_cvt_pk_bf16_f32 v15, v16, v17
	v_lshlrev_b32_e32 v16, 16, v120
	v_and_b32_e32 v17, 0xffff0000, v120
	v_pk_fma_f32 v[10:11], v[10:11], 0.5, v[16:17] op_sel_hi:[1,0,1]
	s_mov_b64 s[24:25], 0x58000
	v_cvt_pk_bf16_f32 v16, v10, v11
	v_lshlrev_b32_e32 v10, 16, v121
	v_and_b32_e32 v11, 0xffff0000, v121
	v_pk_fma_f32 v[10:11], v[12:13], 0.5, v[10:11] op_sel_hi:[1,0,1]
	s_nop 0
	v_cvt_pk_bf16_f32 v17, v10, v11
	v_and_b32_e32 v11, 0xffff0000, v14
	v_lshlrev_b32_e32 v10, 16, v14
	v_mul_f32_e32 v12, v11, v11
	v_fmac_f32_e32 v12, v10, v10
	v_lshlrev_b32_e32 v10, 16, v15
	v_fmac_f32_e32 v12, v10, v10
	v_and_b32_e32 v10, 0xffff0000, v15
	v_fmac_f32_e32 v12, v10, v10
	v_lshlrev_b32_e32 v10, 16, v16
	v_fmac_f32_e32 v12, v10, v10
	v_and_b32_e32 v10, 0xffff0000, v16
	v_fmac_f32_e32 v12, v10, v10
	v_lshlrev_b32_e32 v10, 16, v17
	v_fmac_f32_e32 v12, v10, v10
	v_and_b32_e32 v10, 0xffff0000, v17
	v_fmac_f32_e32 v12, v10, v10
	s_waitcnt vmcnt(14)
	v_lshlrev_b32_e32 v10, 16, v110
	v_and_b32_e32 v11, 0xffff0000, v110
	v_pk_fma_f32 v[6:7], v[6:7], 0.5, v[10:11] op_sel_hi:[1,0,1]
	v_lshlrev_b32_e32 v10, 16, v111
	v_and_b32_e32 v11, 0xffff0000, v111
	v_pk_fma_f32 v[8:9], v[8:9], 0.5, v[10:11] op_sel_hi:[1,0,1]
	v_cvt_pk_bf16_f32 v6, v6, v7
	v_cvt_pk_bf16_f32 v7, v8, v9
	v_lshlrev_b32_e32 v8, 16, v112
	v_and_b32_e32 v9, 0xffff0000, v112
	v_pk_fma_f32 v[2:3], v[2:3], 0.5, v[8:9] op_sel_hi:[1,0,1]
	s_nop 0
	v_cvt_pk_bf16_f32 v8, v2, v3
	v_lshlrev_b32_e32 v2, 16, v113
	v_and_b32_e32 v3, 0xffff0000, v113
	v_pk_fma_f32 v[2:3], v[4:5], 0.5, v[2:3] op_sel_hi:[1,0,1]
	v_lshl_add_u64 v[4:5], v[210:211], 0, s[24:25]
	v_cvt_pk_bf16_f32 v9, v2, v3
	v_and_b32_e32 v3, 0xffff0000, v6
	v_lshlrev_b32_e32 v2, 16, v6
	v_mul_f32_e32 v3, v3, v3
	v_fmac_f32_e32 v3, v2, v2
	v_lshlrev_b32_e32 v2, 16, v7
	v_fmac_f32_e32 v3, v2, v2
	v_and_b32_e32 v2, 0xffff0000, v7
	v_fmac_f32_e32 v3, v2, v2
	v_lshlrev_b32_e32 v2, 16, v8
	v_fmac_f32_e32 v3, v2, v2
	v_and_b32_e32 v2, 0xffff0000, v8
	v_fmac_f32_e32 v3, v2, v2
	v_lshlrev_b32_e32 v2, 16, v9
	v_fmac_f32_e32 v3, v2, v2
	v_and_b32_e32 v2, 0xffff0000, v9
	v_fmac_f32_e32 v3, v2, v2
	v_add_f32_e32 v2, v12, v3
	v_mov_b32_e32 v3, v2
	s_nop 1
	v_permlane16_swap_b32_e32 v3, v2
	s_mov_b64 s[24:25], 0x58100
	v_lshl_add_u64 v[10:11], v[210:211], 0, s[24:25]
	global_store_dwordx4 v[4:5], v[14:17], off
	global_store_dwordx4 v[10:11], v[6:9], off
	s_waitcnt lgkmcnt(0)
	v_add_f32_e32 v2, v2, v3
	v_mov_b32_e32 v3, v2
	s_nop 1
	v_permlane32_swap_b32_e32 v3, v2
	s_and_saveexec_b64 s[24:25], vcc
	s_cbranch_execz .LBB0_239
	s_waitcnt lgkmcnt(0)
	v_add_f32_e32 v2, v2, v3
	v_mul_f32_e32 v2, 0x48800000, v2
	v_cvt_u32_f32_e32 v2, v2
	v_mov_b32_e32 v3, v0
	global_atomic_add_x2 v[126:127], v[2:3], off offset:1408

.LBB0_893:
	v_mov_b32_e32 v110, v218
	s_lshl_b32 s15, s24, 8
	s_add_i32 s15, s15, s44
	v_and_b32_e32 v196, 15, v110
	v_bfe_u32 v197, v110, 4, 2
	v_or_b32_e32 v212, s15, v196
	s_lshl_b32 s15, s22, 8
	v_lshl_or_b32 v110, v197, 3, s15
	v_ashrrev_i32_e32 v213, 31, v212
	v_or_b32_e32 v110, s45, v110
	v_lshlrev_b64 v[112:113], 11, v[212:213]
	v_lshl_add_u64 v[112:113], s[8:9], 0, v[112:113]
	v_ashrrev_i32_e32 v111, 31, v110
	v_lshl_add_u64 v[210:211], v[110:111], 1, v[112:113]
	global_load_dwordx4 v[228:231], v[210:211], off
	global_load_dwordx4 v[186:189], v[210:211], off offset:256
	v_add_co_u32_e32 v110, vcc, s75, v210
	s_mov_b32 s15, 0x58000
	s_nop 0
	v_addc_co_u32_e32 v111, vcc, 0, v211, vcc
	global_load_dwordx4 v[182:185], v[110:111], off
	global_load_dwordx4 v[178:181], v[110:111], off offset:256
	v_add_co_u32_e32 v110, vcc, s71, v210
	v_lshlrev_b32_e32 v198, 6, v197
	s_nop 0
	v_addc_co_u32_e32 v111, vcc, 0, v211, vcc
	global_load_dwordx4 v[174:177], v[110:111], off
	global_load_dwordx4 v[170:173], v[110:111], off offset:256
	v_add_co_u32_e32 v110, vcc, s74, v210
	v_lshlrev_b32_e32 v196, 2, v196
	s_nop 0
	v_addc_co_u32_e32 v111, vcc, 0, v211, vcc
	global_load_dwordx4 v[166:169], v[110:111], off
	global_load_dwordx4 v[162:165], v[110:111], off offset:256
	v_add_co_u32_e32 v110, vcc, s87, v210
	v_bitop3_b32 v216, v198, 64, v196 bitop3:0x36
	s_nop 0
	v_addc_co_u32_e32 v111, vcc, 0, v211, vcc
	global_load_dwordx4 v[154:157], v[110:111], off
	global_load_dwordx4 v[146:149], v[110:111], off offset:256
	v_add_co_u32_e32 v110, vcc, s92, v210
	v_bitop3_b32 v215, v198, s82, v196 bitop3:0x36
	s_nop 0
	v_addc_co_u32_e32 v111, vcc, 0, v211, vcc
	global_load_dwordx4 v[142:145], v[110:111], off
	global_load_dwordx4 v[138:141], v[110:111], off offset:256
	v_add_co_u32_e32 v110, vcc, s93, v210
	s_waitcnt vmcnt(0)
	v_lshlrev_b32_e32 v196, 16, v228
	v_addc_co_u32_e32 v111, vcc, 0, v211, vcc
	global_load_dwordx4 v[134:137], v[110:111], off
	global_load_dwordx4 v[122:125], v[110:111], off offset:256
	v_add_co_u32_e32 v110, vcc, s15, v210
	s_nop 1
	v_addc_co_u32_e32 v111, vcc, 0, v211, vcc
	global_load_dwordx4 v[118:121], v[110:111], off
	s_nop 0
	global_load_dwordx4 v[110:113], v[110:111], off offset:256
	v_cmp_eq_u32_e32 vcc, 0, v197
	v_and_b32_e32 v197, 0xffff0000, v228
	v_pk_add_f32 v[158:159], v[158:159], v[196:197]
	v_lshlrev_b32_e32 v196, 16, v229
	v_and_b32_e32 v197, 0xffff0000, v229
	v_pk_add_f32 v[160:161], v[160:161], v[196:197]
	v_cvt_pk_bf16_f32 v158, v158, v159
	v_cvt_pk_bf16_f32 v159, v160, v161
	v_lshlrev_b32_e32 v160, 16, v230
	v_and_b32_e32 v161, 0xffff0000, v230
	v_pk_add_f32 v[150:151], v[150:151], v[160:161]
	s_nop 0
	v_cvt_pk_bf16_f32 v160, v150, v151
	v_lshlrev_b32_e32 v150, 16, v231
	v_and_b32_e32 v151, 0xffff0000, v231
	v_pk_add_f32 v[150:151], v[152:153], v[150:151]
	s_nop 0
	v_cvt_pk_bf16_f32 v161, v150, v151
	v_and_b32_e32 v151, 0xffff0000, v158
	v_lshlrev_b32_e32 v150, 16, v158
	v_mul_f32_e32 v152, v151, v151
	v_fmac_f32_e32 v152, v150, v150
	v_lshlrev_b32_e32 v150, 16, v159
	v_fmac_f32_e32 v152, v150, v150
	v_and_b32_e32 v150, 0xffff0000, v159
	v_fmac_f32_e32 v152, v150, v150
	v_lshlrev_b32_e32 v150, 16, v160
	v_fmac_f32_e32 v152, v150, v150
	v_and_b32_e32 v150, 0xffff0000, v160
	v_fmac_f32_e32 v152, v150, v150
	v_lshlrev_b32_e32 v150, 16, v161
	v_fmac_f32_e32 v152, v150, v150
	v_and_b32_e32 v150, 0xffff0000, v161
	v_fmac_f32_e32 v152, v150, v150
	v_lshlrev_b32_e32 v150, 16, v186
	v_and_b32_e32 v151, 0xffff0000, v186
	v_pk_add_f32 v[130:131], v[130:131], v[150:151]
	v_lshlrev_b32_e32 v150, 16, v187
	v_and_b32_e32 v151, 0xffff0000, v187
	v_pk_add_f32 v[132:133], v[132:133], v[150:151]
	v_cvt_pk_bf16_f32 v130, v130, v131
	v_cvt_pk_bf16_f32 v131, v132, v133
	v_lshlrev_b32_e32 v132, 16, v188
	v_and_b32_e32 v133, 0xffff0000, v188
	v_pk_add_f32 v[126:127], v[126:127], v[132:133]
	global_store_dwordx4 v[210:211], v[158:161], off
	v_cvt_pk_bf16_f32 v132, v126, v127
	v_lshlrev_b32_e32 v126, 16, v189
	v_and_b32_e32 v127, 0xffff0000, v189
	v_pk_add_f32 v[126:127], v[128:129], v[126:127]
	s_nop 0
	v_cvt_pk_bf16_f32 v133, v126, v127
	v_and_b32_e32 v127, 0xffff0000, v130
	v_lshlrev_b32_e32 v126, 16, v130
	v_mul_f32_e32 v127, v127, v127
	v_fmac_f32_e32 v127, v126, v126
	v_lshlrev_b32_e32 v126, 16, v131
	v_fmac_f32_e32 v127, v126, v126
	v_and_b32_e32 v126, 0xffff0000, v131
	v_fmac_f32_e32 v127, v126, v126
	v_lshlrev_b32_e32 v126, 16, v132
	v_fmac_f32_e32 v127, v126, v126
	v_and_b32_e32 v126, 0xffff0000, v132
	v_fmac_f32_e32 v127, v126, v126
	v_lshlrev_b32_e32 v126, 16, v133
	v_fmac_f32_e32 v127, v126, v126
	v_and_b32_e32 v126, 0xffff0000, v133
	v_fmac_f32_e32 v127, v126, v126
	v_add_f32_e32 v126, v152, v127
	v_mov_b32_e32 v127, v126
	s_nop 1
	v_permlane16_swap_b32_e32 v127, v126
	global_store_dwordx4 v[210:211], v[130:133], off offset:256
	s_waitcnt lgkmcnt(0)
	v_add_f32_e32 v128, v126, v127
	v_mov_b32_e32 v129, v128
	s_nop 1
	v_permlane32_swap_b32_e32 v129, v128
	v_lshl_add_u64 v[126:127], v[212:213], 3, s[10:11]
	s_and_saveexec_b64 s[22:23], vcc
	s_cbranch_execz .LBB0_895
	s_waitcnt lgkmcnt(0)
	v_add_f32_e32 v128, v128, v129
	v_mul_f32_e32 v128, 0x48800000, v128
	v_cvt_u32_f32_e32 v128, v128
	v_mov_b32_e32 v129, v0
	global_atomic_add_x2 v[126:127], v[128:129], off
.LBB0_895:
	s_or_b64 exec, exec, s[22:23]
	v_lshlrev_b32_e32 v128, 16, v182
	s_waitcnt lgkmcnt(0)
	v_and_b32_e32 v129, 0xffff0000, v182
	v_pk_add_f32 v[114:115], v[114:115], v[128:129]
	v_lshlrev_b32_e32 v128, 16, v183
	v_and_b32_e32 v129, 0xffff0000, v183
	v_pk_add_f32 v[116:117], v[116:117], v[128:129]
	v_cvt_pk_bf16_f32 v114, v114, v115
	v_cvt_pk_bf16_f32 v115, v116, v117
	v_lshlrev_b32_e32 v116, 16, v184
	v_and_b32_e32 v117, 0xffff0000, v184
	v_pk_add_f32 v[106:107], v[106:107], v[116:117]
	s_mov_b64 s[22:23], 0x8000
	v_cvt_pk_bf16_f32 v116, v106, v107
	v_lshlrev_b32_e32 v106, 16, v185
	v_and_b32_e32 v107, 0xffff0000, v185
	v_pk_add_f32 v[106:107], v[108:109], v[106:107]
	s_nop 0
	v_cvt_pk_bf16_f32 v117, v106, v107
	v_and_b32_e32 v107, 0xffff0000, v114
	v_lshlrev_b32_e32 v106, 16, v114
	v_mul_f32_e32 v108, v107, v107
	v_fmac_f32_e32 v108, v106, v106
	v_lshlrev_b32_e32 v106, 16, v115
	v_fmac_f32_e32 v108, v106, v106
	v_and_b32_e32 v106, 0xffff0000, v115
	v_fmac_f32_e32 v108, v106, v106
	v_lshlrev_b32_e32 v106, 16, v116
	v_fmac_f32_e32 v108, v106, v106
	v_and_b32_e32 v106, 0xffff0000, v116
	v_fmac_f32_e32 v108, v106, v106
	v_lshlrev_b32_e32 v106, 16, v117
	v_fmac_f32_e32 v108, v106, v106
	v_and_b32_e32 v106, 0xffff0000, v117
	v_fmac_f32_e32 v108, v106, v106
	v_lshlrev_b32_e32 v106, 16, v178
	v_and_b32_e32 v107, 0xffff0000, v178
	v_pk_add_f32 v[102:103], v[102:103], v[106:107]
	v_lshlrev_b32_e32 v106, 16, v179
	v_and_b32_e32 v107, 0xffff0000, v179
	v_pk_add_f32 v[104:105], v[104:105], v[106:107]
	v_cvt_pk_bf16_f32 v102, v102, v103
	v_cvt_pk_bf16_f32 v103, v104, v105
	v_lshlrev_b32_e32 v104, 16, v180
	v_and_b32_e32 v105, 0xffff0000, v180
	v_pk_add_f32 v[98:99], v[98:99], v[104:105]
	s_nop 0
	v_cvt_pk_bf16_f32 v104, v98, v99
	v_lshlrev_b32_e32 v98, 16, v181
	v_and_b32_e32 v99, 0xffff0000, v181
	v_pk_add_f32 v[98:99], v[100:101], v[98:99]
	v_lshl_add_u64 v[100:101], v[210:211], 0, s[22:23]
	v_cvt_pk_bf16_f32 v105, v98, v99
	v_and_b32_e32 v99, 0xffff0000, v102
	v_lshlrev_b32_e32 v98, 16, v102
	v_mul_f32_e32 v99, v99, v99
	v_fmac_f32_e32 v99, v98, v98
	v_lshlrev_b32_e32 v98, 16, v103
	v_fmac_f32_e32 v99, v98, v98
	v_and_b32_e32 v98, 0xffff0000, v103
	v_fmac_f32_e32 v99, v98, v98
	v_lshlrev_b32_e32 v98, 16, v104
	v_fmac_f32_e32 v99, v98, v98
	v_and_b32_e32 v98, 0xffff0000, v104
	v_fmac_f32_e32 v99, v98, v98
	v_lshlrev_b32_e32 v98, 16, v105
	v_fmac_f32_e32 v99, v98, v98
	v_and_b32_e32 v98, 0xffff0000, v105
	v_fmac_f32_e32 v99, v98, v98
	v_add_f32_e32 v98, v108, v99
	v_mov_b32_e32 v99, v98
	s_nop 1
	v_permlane16_swap_b32_e32 v99, v98
	s_mov_b64 s[22:23], 0x8100
	v_lshl_add_u64 v[106:107], v[210:211], 0, s[22:23]
	global_store_dwordx4 v[100:101], v[114:117], off
	global_store_dwordx4 v[106:107], v[102:105], off
	s_waitcnt lgkmcnt(0)
	v_add_f32_e32 v98, v98, v99
	v_mov_b32_e32 v99, v98
	s_nop 1
	v_permlane32_swap_b32_e32 v99, v98
	s_and_saveexec_b64 s[22:23], vcc
	s_cbranch_execz .LBB0_897
	s_waitcnt lgkmcnt(0)
	v_add_f32_e32 v98, v98, v99
	v_mul_f32_e32 v98, 0x48800000, v98
	v_cvt_u32_f32_e32 v98, v98
	v_mov_b32_e32 v99, v0
	global_atomic_add_x2 v[126:127], v[98:99], off offset:128
.LBB0_897:
	s_or_b64 exec, exec, s[22:23]
	v_lshlrev_b32_e32 v98, 16, v174
	s_waitcnt lgkmcnt(0)
	v_and_b32_e32 v99, 0xffff0000, v174
	v_pk_add_f32 v[94:95], v[94:95], v[98:99]
	v_lshlrev_b32_e32 v98, 16, v175
	v_and_b32_e32 v99, 0xffff0000, v175
	v_pk_add_f32 v[96:97], v[96:97], v[98:99]
	v_cvt_pk_bf16_f32 v94, v94, v95
	v_cvt_pk_bf16_f32 v95, v96, v97
	v_lshlrev_b32_e32 v96, 16, v176
	v_and_b32_e32 v97, 0xffff0000, v176
	v_pk_add_f32 v[90:91], v[90:91], v[96:97]
	s_mov_b64 s[22:23], 0x10100
	v_cvt_pk_bf16_f32 v96, v90, v91
	v_lshlrev_b32_e32 v90, 16, v177
	v_and_b32_e32 v91, 0xffff0000, v177
	v_pk_add_f32 v[90:91], v[92:93], v[90:91]
	s_nop 0
	v_cvt_pk_bf16_f32 v97, v90, v91
	v_and_b32_e32 v91, 0xffff0000, v94
	v_lshlrev_b32_e32 v90, 16, v94
	v_mul_f32_e32 v92, v91, v91
	v_fmac_f32_e32 v92, v90, v90
	v_lshlrev_b32_e32 v90, 16, v95
	v_fmac_f32_e32 v92, v90, v90
	v_and_b32_e32 v90, 0xffff0000, v95
	v_fmac_f32_e32 v92, v90, v90
	v_lshlrev_b32_e32 v90, 16, v96
	v_fmac_f32_e32 v92, v90, v90
	v_and_b32_e32 v90, 0xffff0000, v96
	v_fmac_f32_e32 v92, v90, v90
	v_lshlrev_b32_e32 v90, 16, v97
	v_fmac_f32_e32 v92, v90, v90
	v_and_b32_e32 v90, 0xffff0000, v97
	v_fmac_f32_e32 v92, v90, v90
	v_lshlrev_b32_e32 v90, 16, v170
	v_and_b32_e32 v91, 0xffff0000, v170
	v_pk_add_f32 v[86:87], v[86:87], v[90:91]
	v_lshlrev_b32_e32 v90, 16, v171
	v_and_b32_e32 v91, 0xffff0000, v171
	v_pk_add_f32 v[88:89], v[88:89], v[90:91]
	v_cvt_pk_bf16_f32 v86, v86, v87
	v_cvt_pk_bf16_f32 v87, v88, v89
	v_lshlrev_b32_e32 v88, 16, v172
	v_and_b32_e32 v89, 0xffff0000, v172
	v_pk_add_f32 v[82:83], v[82:83], v[88:89]
	v_lshl_add_u64 v[90:91], v[210:211], 0, s[22:23]
	v_cvt_pk_bf16_f32 v88, v82, v83
	v_lshlrev_b32_e32 v82, 16, v173
	v_and_b32_e32 v83, 0xffff0000, v173
	v_pk_add_f32 v[82:83], v[84:85], v[82:83]
	v_lshl_add_u64 v[84:85], v[210:211], 0, s[90:91]
	v_cvt_pk_bf16_f32 v89, v82, v83
	v_and_b32_e32 v83, 0xffff0000, v86
	v_lshlrev_b32_e32 v82, 16, v86
	v_mul_f32_e32 v83, v83, v83
	v_fmac_f32_e32 v83, v82, v82
	v_lshlrev_b32_e32 v82, 16, v87
	v_fmac_f32_e32 v83, v82, v82
	v_and_b32_e32 v82, 0xffff0000, v87
	v_fmac_f32_e32 v83, v82, v82
	v_lshlrev_b32_e32 v82, 16, v88
	v_fmac_f32_e32 v83, v82, v82
	v_and_b32_e32 v82, 0xffff0000, v88
	v_fmac_f32_e32 v83, v82, v82
	v_lshlrev_b32_e32 v82, 16, v89
	v_fmac_f32_e32 v83, v82, v82
	v_and_b32_e32 v82, 0xffff0000, v89
	v_fmac_f32_e32 v83, v82, v82
	v_add_f32_e32 v82, v92, v83
	v_mov_b32_e32 v83, v82
	s_nop 1
	v_permlane16_swap_b32_e32 v83, v82
	global_store_dwordx4 v[84:85], v[94:97], off
	global_store_dwordx4 v[90:91], v[86:89], off
	s_waitcnt lgkmcnt(0)
	v_add_f32_e32 v82, v82, v83
	v_mov_b32_e32 v83, v82
	s_nop 1
	v_permlane32_swap_b32_e32 v83, v82
	s_and_saveexec_b64 s[22:23], vcc
	s_cbranch_execz .LBB0_899
	s_waitcnt lgkmcnt(0)
	v_add_f32_e32 v82, v82, v83
	v_mul_f32_e32 v82, 0x48800000, v82
	v_cvt_u32_f32_e32 v82, v82
	v_mov_b32_e32 v83, v0
	global_atomic_add_x2 v[126:127], v[82:83], off offset:256
.LBB0_899:
	s_or_b64 exec, exec, s[22:23]
	v_lshlrev_b32_e32 v82, 16, v166
	s_waitcnt lgkmcnt(0)
	v_and_b32_e32 v83, 0xffff0000, v166
	v_pk_add_f32 v[78:79], v[78:79], v[82:83]
	v_lshlrev_b32_e32 v82, 16, v167
	v_and_b32_e32 v83, 0xffff0000, v167
	v_pk_add_f32 v[80:81], v[80:81], v[82:83]
	v_cvt_pk_bf16_f32 v78, v78, v79
	v_cvt_pk_bf16_f32 v79, v80, v81
	v_lshlrev_b32_e32 v80, 16, v168
	v_and_b32_e32 v81, 0xffff0000, v168
	v_pk_add_f32 v[74:75], v[74:75], v[80:81]
	s_mov_b64 s[22:23], 0x18000
	v_cvt_pk_bf16_f32 v80, v74, v75
	v_lshlrev_b32_e32 v74, 16, v169
	v_and_b32_e32 v75, 0xffff0000, v169
	v_pk_add_f32 v[74:75], v[76:77], v[74:75]
	s_nop 0
	v_cvt_pk_bf16_f32 v81, v74, v75
	v_and_b32_e32 v75, 0xffff0000, v78
	v_lshlrev_b32_e32 v74, 16, v78
	v_mul_f32_e32 v76, v75, v75
	v_fmac_f32_e32 v76, v74, v74
	v_lshlrev_b32_e32 v74, 16, v79
	v_fmac_f32_e32 v76, v74, v74
	v_and_b32_e32 v74, 0xffff0000, v79
	v_fmac_f32_e32 v76, v74, v74
	v_lshlrev_b32_e32 v74, 16, v80
	v_fmac_f32_e32 v76, v74, v74
	v_and_b32_e32 v74, 0xffff0000, v80
	v_fmac_f32_e32 v76, v74, v74
	v_lshlrev_b32_e32 v74, 16, v81
	v_fmac_f32_e32 v76, v74, v74
	v_and_b32_e32 v74, 0xffff0000, v81
	v_fmac_f32_e32 v76, v74, v74
	v_lshlrev_b32_e32 v74, 16, v162
	v_and_b32_e32 v75, 0xffff0000, v162
	v_pk_add_f32 v[70:71], v[70:71], v[74:75]
	v_lshlrev_b32_e32 v74, 16, v163
	v_and_b32_e32 v75, 0xffff0000, v163
	v_pk_add_f32 v[72:73], v[72:73], v[74:75]
	v_cvt_pk_bf16_f32 v70, v70, v71
	v_cvt_pk_bf16_f32 v71, v72, v73
	v_lshlrev_b32_e32 v72, 16, v164
	v_and_b32_e32 v73, 0xffff0000, v164
	v_pk_add_f32 v[66:67], v[66:67], v[72:73]
	s_nop 0
	v_cvt_pk_bf16_f32 v72, v66, v67
	v_lshlrev_b32_e32 v66, 16, v165
	v_and_b32_e32 v67, 0xffff0000, v165
	v_pk_add_f32 v[66:67], v[68:69], v[66:67]
	v_lshl_add_u64 v[68:69], v[210:211], 0, s[22:23]
	v_cvt_pk_bf16_f32 v73, v66, v67
	v_and_b32_e32 v67, 0xffff0000, v70
	v_lshlrev_b32_e32 v66, 16, v70
	v_mul_f32_e32 v67, v67, v67
	v_fmac_f32_e32 v67, v66, v66
	v_lshlrev_b32_e32 v66, 16, v71
	v_fmac_f32_e32 v67, v66, v66
	v_and_b32_e32 v66, 0xffff0000, v71
	v_fmac_f32_e32 v67, v66, v66
	v_lshlrev_b32_e32 v66, 16, v72
	v_fmac_f32_e32 v67, v66, v66
	v_and_b32_e32 v66, 0xffff0000, v72
	v_fmac_f32_e32 v67, v66, v66
	v_lshlrev_b32_e32 v66, 16, v73
	v_fmac_f32_e32 v67, v66, v66
	v_and_b32_e32 v66, 0xffff0000, v73
	v_fmac_f32_e32 v67, v66, v66
	v_add_f32_e32 v66, v76, v67
	v_mov_b32_e32 v67, v66
	s_nop 1
	v_permlane16_swap_b32_e32 v67, v66
	s_mov_b64 s[22:23], 0x18100
	v_lshl_add_u64 v[74:75], v[210:211], 0, s[22:23]
	global_store_dwordx4 v[68:69], v[78:81], off
	global_store_dwordx4 v[74:75], v[70:73], off
	s_waitcnt lgkmcnt(0)
	v_add_f32_e32 v66, v66, v67
	v_mov_b32_e32 v67, v66
	s_nop 1
	v_permlane32_swap_b32_e32 v67, v66
	s_and_saveexec_b64 s[22:23], vcc
	s_cbranch_execz .LBB0_901
	s_waitcnt lgkmcnt(0)
	v_add_f32_e32 v66, v66, v67
	v_mul_f32_e32 v66, 0x48800000, v66
	v_cvt_u32_f32_e32 v66, v66
	v_mov_b32_e32 v67, v0
	global_atomic_add_x2 v[126:127], v[66:67], off offset:384
.LBB0_901:
	s_or_b64 exec, exec, s[22:23]
	v_lshlrev_b32_e32 v66, 16, v154
	s_waitcnt lgkmcnt(0)
	v_and_b32_e32 v67, 0xffff0000, v154
	v_pk_add_f32 v[62:63], v[62:63], v[66:67]
	v_lshlrev_b32_e32 v66, 16, v155
	v_and_b32_e32 v67, 0xffff0000, v155
	v_pk_add_f32 v[64:65], v[64:65], v[66:67]
	v_cvt_pk_bf16_f32 v62, v62, v63
	v_cvt_pk_bf16_f32 v63, v64, v65
	v_lshlrev_b32_e32 v64, 16, v156
	v_and_b32_e32 v65, 0xffff0000, v156
	v_pk_add_f32 v[58:59], v[58:59], v[64:65]
	s_mov_b64 s[22:23], 0x40100
	v_cvt_pk_bf16_f32 v64, v58, v59
	v_lshlrev_b32_e32 v58, 16, v157
	v_and_b32_e32 v59, 0xffff0000, v157
	v_pk_add_f32 v[58:59], v[60:61], v[58:59]
	s_nop 0
	v_cvt_pk_bf16_f32 v65, v58, v59
	v_and_b32_e32 v59, 0xffff0000, v62
	v_lshlrev_b32_e32 v58, 16, v62
	v_mul_f32_e32 v60, v59, v59
	v_fmac_f32_e32 v60, v58, v58
	v_lshlrev_b32_e32 v58, 16, v63
	v_fmac_f32_e32 v60, v58, v58
	v_and_b32_e32 v58, 0xffff0000, v63
	v_fmac_f32_e32 v60, v58, v58
	v_lshlrev_b32_e32 v58, 16, v64
	v_fmac_f32_e32 v60, v58, v58
	v_and_b32_e32 v58, 0xffff0000, v64
	v_fmac_f32_e32 v60, v58, v58
	v_lshlrev_b32_e32 v58, 16, v65
	v_fmac_f32_e32 v60, v58, v58
	v_and_b32_e32 v58, 0xffff0000, v65
	v_fmac_f32_e32 v60, v58, v58
	v_lshlrev_b32_e32 v58, 16, v146
	v_and_b32_e32 v59, 0xffff0000, v146
	v_pk_add_f32 v[54:55], v[54:55], v[58:59]
	v_lshlrev_b32_e32 v58, 16, v147
	v_and_b32_e32 v59, 0xffff0000, v147
	v_pk_add_f32 v[56:57], v[56:57], v[58:59]
	v_cvt_pk_bf16_f32 v54, v54, v55
	v_cvt_pk_bf16_f32 v55, v56, v57
	v_lshlrev_b32_e32 v56, 16, v148
	v_and_b32_e32 v57, 0xffff0000, v148
	v_pk_add_f32 v[50:51], v[50:51], v[56:57]
	v_lshl_add_u64 v[58:59], v[210:211], 0, s[22:23]
	v_cvt_pk_bf16_f32 v56, v50, v51
	v_lshlrev_b32_e32 v50, 16, v149
	v_and_b32_e32 v51, 0xffff0000, v149
	v_pk_add_f32 v[50:51], v[52:53], v[50:51]
	v_lshl_add_u64 v[52:53], v[210:211], 0, s[72:73]
	v_cvt_pk_bf16_f32 v57, v50, v51
	v_and_b32_e32 v51, 0xffff0000, v54
	v_lshlrev_b32_e32 v50, 16, v54
	v_mul_f32_e32 v51, v51, v51
	v_fmac_f32_e32 v51, v50, v50
	v_lshlrev_b32_e32 v50, 16, v55
	v_fmac_f32_e32 v51, v50, v50
	v_and_b32_e32 v50, 0xffff0000, v55
	v_fmac_f32_e32 v51, v50, v50
	v_lshlrev_b32_e32 v50, 16, v56
	v_fmac_f32_e32 v51, v50, v50
	v_and_b32_e32 v50, 0xffff0000, v56
	v_fmac_f32_e32 v51, v50, v50
	v_lshlrev_b32_e32 v50, 16, v57
	v_fmac_f32_e32 v51, v50, v50
	v_and_b32_e32 v50, 0xffff0000, v57
	v_fmac_f32_e32 v51, v50, v50
	v_add_f32_e32 v50, v60, v51
	v_mov_b32_e32 v51, v50
	s_nop 1
	v_permlane16_swap_b32_e32 v51, v50
	global_store_dwordx4 v[52:53], v[62:65], off
	global_store_dwordx4 v[58:59], v[54:57], off
	s_waitcnt lgkmcnt(0)
	v_add_f32_e32 v50, v50, v51
	v_mov_b32_e32 v51, v50
	s_nop 1
	v_permlane32_swap_b32_e32 v51, v50
	s_and_saveexec_b64 s[22:23], vcc
	s_cbranch_execz .LBB0_903
	s_waitcnt lgkmcnt(0)
	v_add_f32_e32 v50, v50, v51
	v_mul_f32_e32 v50, 0x48800000, v50
	v_cvt_u32_f32_e32 v50, v50
	v_mov_b32_e32 v51, v0
	global_atomic_add_x2 v[126:127], v[50:51], off offset:1024
.LBB0_903:
	s_or_b64 exec, exec, s[22:23]
	v_lshlrev_b32_e32 v50, 16, v142
	s_waitcnt lgkmcnt(0)
	v_and_b32_e32 v51, 0xffff0000, v142
	v_pk_add_f32 v[46:47], v[46:47], v[50:51]
	v_lshlrev_b32_e32 v50, 16, v143
	v_and_b32_e32 v51, 0xffff0000, v143
	v_pk_add_f32 v[48:49], v[48:49], v[50:51]
	v_cvt_pk_bf16_f32 v46, v46, v47
	v_cvt_pk_bf16_f32 v47, v48, v49
	v_lshlrev_b32_e32 v48, 16, v144
	v_and_b32_e32 v49, 0xffff0000, v144
	v_pk_add_f32 v[42:43], v[42:43], v[48:49]
	s_mov_b64 s[22:23], 0x48000
	v_cvt_pk_bf16_f32 v48, v42, v43
	v_lshlrev_b32_e32 v42, 16, v145
	v_and_b32_e32 v43, 0xffff0000, v145
	v_pk_add_f32 v[42:43], v[44:45], v[42:43]
	s_nop 0
	v_cvt_pk_bf16_f32 v49, v42, v43
	v_and_b32_e32 v43, 0xffff0000, v46
	v_lshlrev_b32_e32 v42, 16, v46
	v_mul_f32_e32 v44, v43, v43
	v_fmac_f32_e32 v44, v42, v42
	v_lshlrev_b32_e32 v42, 16, v47
	v_fmac_f32_e32 v44, v42, v42
	v_and_b32_e32 v42, 0xffff0000, v47
	v_fmac_f32_e32 v44, v42, v42
	v_lshlrev_b32_e32 v42, 16, v48
	v_fmac_f32_e32 v44, v42, v42
	v_and_b32_e32 v42, 0xffff0000, v48
	v_fmac_f32_e32 v44, v42, v42
	v_lshlrev_b32_e32 v42, 16, v49
	v_fmac_f32_e32 v44, v42, v42
	v_and_b32_e32 v42, 0xffff0000, v49
	v_fmac_f32_e32 v44, v42, v42
	v_lshlrev_b32_e32 v42, 16, v138
	v_and_b32_e32 v43, 0xffff0000, v138
	v_pk_add_f32 v[38:39], v[38:39], v[42:43]
	v_lshlrev_b32_e32 v42, 16, v139
	v_and_b32_e32 v43, 0xffff0000, v139
	v_pk_add_f32 v[40:41], v[40:41], v[42:43]
	v_cvt_pk_bf16_f32 v38, v38, v39
	v_cvt_pk_bf16_f32 v39, v40, v41
	v_lshlrev_b32_e32 v40, 16, v140
	v_and_b32_e32 v41, 0xffff0000, v140
	v_pk_add_f32 v[34:35], v[34:35], v[40:41]
	s_nop 0
	v_cvt_pk_bf16_f32 v40, v34, v35
	v_lshlrev_b32_e32 v34, 16, v141
	v_and_b32_e32 v35, 0xffff0000, v141
	v_pk_add_f32 v[34:35], v[36:37], v[34:35]
	v_lshl_add_u64 v[36:37], v[210:211], 0, s[22:23]
	v_cvt_pk_bf16_f32 v41, v34, v35
	v_and_b32_e32 v35, 0xffff0000, v38
	v_lshlrev_b32_e32 v34, 16, v38
	v_mul_f32_e32 v35, v35, v35
	v_fmac_f32_e32 v35, v34, v34
	v_lshlrev_b32_e32 v34, 16, v39
	v_fmac_f32_e32 v35, v34, v34
	v_and_b32_e32 v34, 0xffff0000, v39
	v_fmac_f32_e32 v35, v34, v34
	v_lshlrev_b32_e32 v34, 16, v40
	v_fmac_f32_e32 v35, v34, v34
	v_and_b32_e32 v34, 0xffff0000, v40
	v_fmac_f32_e32 v35, v34, v34
	v_lshlrev_b32_e32 v34, 16, v41
	v_fmac_f32_e32 v35, v34, v34
	v_and_b32_e32 v34, 0xffff0000, v41
	v_fmac_f32_e32 v35, v34, v34
	v_add_f32_e32 v34, v44, v35
	v_mov_b32_e32 v35, v34
	s_nop 1
	v_permlane16_swap_b32_e32 v35, v34
	s_mov_b64 s[22:23], 0x48100
	v_lshl_add_u64 v[42:43], v[210:211], 0, s[22:23]
	global_store_dwordx4 v[36:37], v[46:49], off
	global_store_dwordx4 v[42:43], v[38:41], off
	s_waitcnt lgkmcnt(0)
	v_add_f32_e32 v34, v34, v35
	v_mov_b32_e32 v35, v34
	s_nop 1
	v_permlane32_swap_b32_e32 v35, v34
	s_and_saveexec_b64 s[22:23], vcc
	s_cbranch_execz .LBB0_905
	s_waitcnt lgkmcnt(0)
	v_add_f32_e32 v34, v34, v35
	v_mul_f32_e32 v34, 0x48800000, v34
	v_cvt_u32_f32_e32 v34, v34
	v_mov_b32_e32 v35, v0
	global_atomic_add_x2 v[126:127], v[34:35], off offset:1152
.LBB0_905:
	s_or_b64 exec, exec, s[22:23]
	s_waitcnt vmcnt(15)
	v_lshlrev_b32_e32 v34, 16, v134
	s_waitcnt lgkmcnt(0)
	v_and_b32_e32 v35, 0xffff0000, v134
	v_pk_add_f32 v[30:31], v[30:31], v[34:35]
	v_lshlrev_b32_e32 v34, 16, v135
	v_and_b32_e32 v35, 0xffff0000, v135
	v_pk_add_f32 v[32:33], v[32:33], v[34:35]
	v_cvt_pk_bf16_f32 v30, v30, v31
	v_cvt_pk_bf16_f32 v31, v32, v33
	v_lshlrev_b32_e32 v32, 16, v136
	v_and_b32_e32 v33, 0xffff0000, v136
	v_pk_add_f32 v[26:27], v[26:27], v[32:33]
	s_mov_b64 s[22:23], 0x50000
	v_cvt_pk_bf16_f32 v32, v26, v27
	v_lshlrev_b32_e32 v26, 16, v137
	v_and_b32_e32 v27, 0xffff0000, v137
	v_pk_add_f32 v[26:27], v[28:29], v[26:27]
	s_nop 0
	v_cvt_pk_bf16_f32 v33, v26, v27
	v_and_b32_e32 v27, 0xffff0000, v30
	v_lshlrev_b32_e32 v26, 16, v30
	v_mul_f32_e32 v28, v27, v27
	v_fmac_f32_e32 v28, v26, v26
	v_lshlrev_b32_e32 v26, 16, v31
	v_fmac_f32_e32 v28, v26, v26
	v_and_b32_e32 v26, 0xffff0000, v31
	v_fmac_f32_e32 v28, v26, v26
	v_lshlrev_b32_e32 v26, 16, v32
	v_fmac_f32_e32 v28, v26, v26
	v_and_b32_e32 v26, 0xffff0000, v32
	v_fmac_f32_e32 v28, v26, v26
	v_lshlrev_b32_e32 v26, 16, v33
	v_fmac_f32_e32 v28, v26, v26
	v_and_b32_e32 v26, 0xffff0000, v33
	v_fmac_f32_e32 v28, v26, v26
	s_waitcnt vmcnt(14)
	v_lshlrev_b32_e32 v26, 16, v122
	v_and_b32_e32 v27, 0xffff0000, v122
	v_pk_add_f32 v[22:23], v[22:23], v[26:27]
	v_lshlrev_b32_e32 v26, 16, v123
	v_and_b32_e32 v27, 0xffff0000, v123
	v_pk_add_f32 v[24:25], v[24:25], v[26:27]
	v_cvt_pk_bf16_f32 v22, v22, v23
	v_cvt_pk_bf16_f32 v23, v24, v25
	v_lshlrev_b32_e32 v24, 16, v124
	v_and_b32_e32 v25, 0xffff0000, v124
	v_pk_add_f32 v[18:19], v[18:19], v[24:25]
	s_nop 0
	v_cvt_pk_bf16_f32 v24, v18, v19
	v_lshlrev_b32_e32 v18, 16, v125
	v_and_b32_e32 v19, 0xffff0000, v125
	v_pk_add_f32 v[18:19], v[20:21], v[18:19]
	v_lshl_add_u64 v[20:21], v[210:211], 0, s[22:23]
	v_cvt_pk_bf16_f32 v25, v18, v19
	v_and_b32_e32 v19, 0xffff0000, v22
	v_lshlrev_b32_e32 v18, 16, v22
	v_mul_f32_e32 v19, v19, v19
	v_fmac_f32_e32 v19, v18, v18
	v_lshlrev_b32_e32 v18, 16, v23
	v_fmac_f32_e32 v19, v18, v18
	v_and_b32_e32 v18, 0xffff0000, v23
	v_fmac_f32_e32 v19, v18, v18
	v_lshlrev_b32_e32 v18, 16, v24
	v_fmac_f32_e32 v19, v18, v18
	v_and_b32_e32 v18, 0xffff0000, v24
	v_fmac_f32_e32 v19, v18, v18
	v_lshlrev_b32_e32 v18, 16, v25
	v_fmac_f32_e32 v19, v18, v18
	v_and_b32_e32 v18, 0xffff0000, v25
	v_fmac_f32_e32 v19, v18, v18
	v_add_f32_e32 v18, v28, v19
	v_mov_b32_e32 v19, v18
	s_nop 1
	v_permlane16_swap_b32_e32 v19, v18
	s_mov_b64 s[22:23], 0x50100
	v_lshl_add_u64 v[26:27], v[210:211], 0, s[22:23]
	global_store_dwordx4 v[20:21], v[30:33], off
	global_store_dwordx4 v[26:27], v[22:25], off
	s_waitcnt lgkmcnt(0)
	v_add_f32_e32 v18, v18, v19
	v_mov_b32_e32 v19, v18
	s_nop 1
	v_permlane32_swap_b32_e32 v19, v18
	s_and_saveexec_b64 s[22:23], vcc
	s_cbranch_execz .LBB0_907
	s_waitcnt lgkmcnt(0)
	v_add_f32_e32 v18, v18, v19
	v_mul_f32_e32 v18, 0x48800000, v18
	v_cvt_u32_f32_e32 v18, v18
	v_mov_b32_e32 v19, v0
	global_atomic_add_x2 v[126:127], v[18:19], off offset:1280
.LBB0_907:
	s_or_b64 exec, exec, s[22:23]
	s_waitcnt vmcnt(15)
	v_lshlrev_b32_e32 v18, 16, v118
	s_waitcnt lgkmcnt(0)
	v_and_b32_e32 v19, 0xffff0000, v118
	v_pk_add_f32 v[14:15], v[14:15], v[18:19]
	v_lshlrev_b32_e32 v18, 16, v119
	v_and_b32_e32 v19, 0xffff0000, v119
	v_pk_add_f32 v[16:17], v[16:17], v[18:19]
	v_cvt_pk_bf16_f32 v14, v14, v15
	v_cvt_pk_bf16_f32 v15, v16, v17
	v_lshlrev_b32_e32 v16, 16, v120
	v_and_b32_e32 v17, 0xffff0000, v120
	v_pk_add_f32 v[10:11], v[10:11], v[16:17]
	s_mov_b64 s[22:23], 0x58000
	v_cvt_pk_bf16_f32 v16, v10, v11
	v_lshlrev_b32_e32 v10, 16, v121
	v_and_b32_e32 v11, 0xffff0000, v121
	v_pk_add_f32 v[10:11], v[12:13], v[10:11]
	s_nop 0
	v_cvt_pk_bf16_f32 v17, v10, v11
	v_and_b32_e32 v11, 0xffff0000, v14
	v_lshlrev_b32_e32 v10, 16, v14
	v_mul_f32_e32 v12, v11, v11
	v_fmac_f32_e32 v12, v10, v10
	v_lshlrev_b32_e32 v10, 16, v15
	v_fmac_f32_e32 v12, v10, v10
	v_and_b32_e32 v10, 0xffff0000, v15
	v_fmac_f32_e32 v12, v10, v10
	v_lshlrev_b32_e32 v10, 16, v16
	v_fmac_f32_e32 v12, v10, v10
	v_and_b32_e32 v10, 0xffff0000, v16
	v_fmac_f32_e32 v12, v10, v10
	v_lshlrev_b32_e32 v10, 16, v17
	v_fmac_f32_e32 v12, v10, v10
	v_and_b32_e32 v10, 0xffff0000, v17
	v_fmac_f32_e32 v12, v10, v10
	s_waitcnt vmcnt(14)
	v_lshlrev_b32_e32 v10, 16, v110
	v_and_b32_e32 v11, 0xffff0000, v110
	v_pk_add_f32 v[6:7], v[6:7], v[10:11]
	v_lshlrev_b32_e32 v10, 16, v111
	v_and_b32_e32 v11, 0xffff0000, v111
	v_pk_add_f32 v[8:9], v[8:9], v[10:11]
	v_cvt_pk_bf16_f32 v6, v6, v7
	v_cvt_pk_bf16_f32 v7, v8, v9
	v_lshlrev_b32_e32 v8, 16, v112
	v_and_b32_e32 v9, 0xffff0000, v112
	v_pk_add_f32 v[2:3], v[2:3], v[8:9]
	s_nop 0
	v_cvt_pk_bf16_f32 v8, v2, v3
	v_lshlrev_b32_e32 v2, 16, v113
	v_and_b32_e32 v3, 0xffff0000, v113
	v_pk_add_f32 v[2:3], v[4:5], v[2:3]
	v_lshl_add_u64 v[4:5], v[210:211], 0, s[22:23]
	v_cvt_pk_bf16_f32 v9, v2, v3
	v_and_b32_e32 v3, 0xffff0000, v6
	v_lshlrev_b32_e32 v2, 16, v6
	v_mul_f32_e32 v3, v3, v3
	v_fmac_f32_e32 v3, v2, v2
	v_lshlrev_b32_e32 v2, 16, v7
	v_fmac_f32_e32 v3, v2, v2
	v_and_b32_e32 v2, 0xffff0000, v7
	v_fmac_f32_e32 v3, v2, v2
	v_lshlrev_b32_e32 v2, 16, v8
	v_fmac_f32_e32 v3, v2, v2
	v_and_b32_e32 v2, 0xffff0000, v8
	v_fmac_f32_e32 v3, v2, v2
	v_lshlrev_b32_e32 v2, 16, v9
	v_fmac_f32_e32 v3, v2, v2
	v_and_b32_e32 v2, 0xffff0000, v9
	v_fmac_f32_e32 v3, v2, v2
	v_add_f32_e32 v2, v12, v3
	v_mov_b32_e32 v3, v2
	s_nop 1
	v_permlane16_swap_b32_e32 v3, v2
	s_mov_b64 s[22:23], 0x58100
	v_lshl_add_u64 v[10:11], v[210:211], 0, s[22:23]
	global_store_dwordx4 v[4:5], v[14:17], off
	global_store_dwordx4 v[10:11], v[6:9], off
	s_waitcnt lgkmcnt(0)
	v_add_f32_e32 v2, v2, v3
	v_mov_b32_e32 v3, v2
	s_nop 1
	v_permlane32_swap_b32_e32 v3, v2
	s_and_saveexec_b64 s[22:23], vcc
	s_cbranch_execz .LBB0_909
	s_waitcnt lgkmcnt(0)
	v_add_f32_e32 v2, v2, v3
	v_mul_f32_e32 v2, 0x48800000, v2
	v_cvt_u32_f32_e32 v2, v2
	v_mov_b32_e32 v3, v0
	global_atomic_add_x2 v[126:127], v[2:3], off offset:1408

.LBB0_1099:
	v_mov_b32_e32 v110, v218
	s_lshl_b32 s4, s26, 8
	s_add_i32 s4, s4, s43
	v_and_b32_e32 v196, 15, v110
	v_bfe_u32 v197, v110, 4, 2
	v_or_b32_e32 v212, s4, v196
	s_lshl_b32 s4, s24, 8
	v_lshl_or_b32 v110, v197, 3, s4
	v_ashrrev_i32_e32 v213, 31, v212
	v_or_b32_e32 v110, s44, v110
	v_lshlrev_b64 v[112:113], 11, v[212:213]
	v_lshl_add_u64 v[112:113], s[10:11], 0, v[112:113]
	v_ashrrev_i32_e32 v111, 31, v110
	v_lshl_add_u64 v[210:211], v[110:111], 1, v[112:113]
	global_load_dwordx4 v[228:231], v[210:211], off
	global_load_dwordx4 v[186:189], v[210:211], off offset:256
	v_add_co_u32_e32 v110, vcc, s75, v210
	s_mov_b32 s4, 0x58000
	s_nop 0
	v_addc_co_u32_e32 v111, vcc, 0, v211, vcc
	global_load_dwordx4 v[182:185], v[110:111], off
	global_load_dwordx4 v[178:181], v[110:111], off offset:256
	v_add_co_u32_e32 v110, vcc, s71, v210
	v_lshlrev_b32_e32 v198, 6, v197
	s_nop 0
	v_addc_co_u32_e32 v111, vcc, 0, v211, vcc
	global_load_dwordx4 v[174:177], v[110:111], off
	global_load_dwordx4 v[170:173], v[110:111], off offset:256
	v_add_co_u32_e32 v110, vcc, s74, v210
	v_lshlrev_b32_e32 v196, 2, v196
	s_nop 0
	v_addc_co_u32_e32 v111, vcc, 0, v211, vcc
	global_load_dwordx4 v[166:169], v[110:111], off
	global_load_dwordx4 v[162:165], v[110:111], off offset:256
	v_add_co_u32_e32 v110, vcc, s87, v210
	v_bitop3_b32 v216, v198, 64, v196 bitop3:0x36
	s_nop 0
	v_addc_co_u32_e32 v111, vcc, 0, v211, vcc
	global_load_dwordx4 v[154:157], v[110:111], off
	global_load_dwordx4 v[146:149], v[110:111], off offset:256
	v_add_co_u32_e32 v110, vcc, s92, v210
	v_bitop3_b32 v215, v198, s82, v196 bitop3:0x36
	s_nop 0
	v_addc_co_u32_e32 v111, vcc, 0, v211, vcc
	global_load_dwordx4 v[142:145], v[110:111], off
	global_load_dwordx4 v[138:141], v[110:111], off offset:256
	v_add_co_u32_e32 v110, vcc, s93, v210
	s_waitcnt vmcnt(0)
	v_lshlrev_b32_e32 v196, 16, v228
	v_addc_co_u32_e32 v111, vcc, 0, v211, vcc
	global_load_dwordx4 v[134:137], v[110:111], off
	global_load_dwordx4 v[122:125], v[110:111], off offset:256
	v_add_co_u32_e32 v110, vcc, s4, v210
	s_nop 1
	v_addc_co_u32_e32 v111, vcc, 0, v211, vcc
	global_load_dwordx4 v[118:121], v[110:111], off
	s_nop 0
	global_load_dwordx4 v[110:113], v[110:111], off offset:256
	v_cmp_eq_u32_e32 vcc, 0, v197
	v_and_b32_e32 v197, 0xffff0000, v228
	v_pk_add_f32 v[158:159], v[158:159], v[196:197]
	v_lshlrev_b32_e32 v196, 16, v229
	v_and_b32_e32 v197, 0xffff0000, v229
	v_pk_add_f32 v[160:161], v[160:161], v[196:197]
	v_cvt_pk_bf16_f32 v158, v158, v159
	v_cvt_pk_bf16_f32 v159, v160, v161
	v_lshlrev_b32_e32 v160, 16, v230
	v_and_b32_e32 v161, 0xffff0000, v230
	v_pk_add_f32 v[150:151], v[150:151], v[160:161]
	s_nop 0
	v_cvt_pk_bf16_f32 v160, v150, v151
	v_lshlrev_b32_e32 v150, 16, v231
	v_and_b32_e32 v151, 0xffff0000, v231
	v_pk_add_f32 v[150:151], v[152:153], v[150:151]
	s_nop 0
	v_cvt_pk_bf16_f32 v161, v150, v151
	v_and_b32_e32 v151, 0xffff0000, v158
	v_lshlrev_b32_e32 v150, 16, v158
	v_mul_f32_e32 v152, v151, v151
	v_fmac_f32_e32 v152, v150, v150
	v_lshlrev_b32_e32 v150, 16, v159
	v_fmac_f32_e32 v152, v150, v150
	v_and_b32_e32 v150, 0xffff0000, v159
	v_fmac_f32_e32 v152, v150, v150
	v_lshlrev_b32_e32 v150, 16, v160
	v_fmac_f32_e32 v152, v150, v150
	v_and_b32_e32 v150, 0xffff0000, v160
	v_fmac_f32_e32 v152, v150, v150
	v_lshlrev_b32_e32 v150, 16, v161
	v_fmac_f32_e32 v152, v150, v150
	v_and_b32_e32 v150, 0xffff0000, v161
	v_fmac_f32_e32 v152, v150, v150
	v_lshlrev_b32_e32 v150, 16, v186
	v_and_b32_e32 v151, 0xffff0000, v186
	v_pk_add_f32 v[130:131], v[130:131], v[150:151]
	v_lshlrev_b32_e32 v150, 16, v187
	v_and_b32_e32 v151, 0xffff0000, v187
	v_pk_add_f32 v[132:133], v[132:133], v[150:151]
	v_cvt_pk_bf16_f32 v130, v130, v131
	v_cvt_pk_bf16_f32 v131, v132, v133
	v_lshlrev_b32_e32 v132, 16, v188
	v_and_b32_e32 v133, 0xffff0000, v188
	v_pk_add_f32 v[126:127], v[126:127], v[132:133]
	global_store_dwordx4 v[210:211], v[158:161], off
	v_cvt_pk_bf16_f32 v132, v126, v127
	v_lshlrev_b32_e32 v126, 16, v189
	v_and_b32_e32 v127, 0xffff0000, v189
	v_pk_add_f32 v[126:127], v[128:129], v[126:127]
	s_nop 0
	v_cvt_pk_bf16_f32 v133, v126, v127
	v_and_b32_e32 v127, 0xffff0000, v130
	v_lshlrev_b32_e32 v126, 16, v130
	v_mul_f32_e32 v127, v127, v127
	v_fmac_f32_e32 v127, v126, v126
	v_lshlrev_b32_e32 v126, 16, v131
	v_fmac_f32_e32 v127, v126, v126
	v_and_b32_e32 v126, 0xffff0000, v131
	v_fmac_f32_e32 v127, v126, v126
	v_lshlrev_b32_e32 v126, 16, v132
	v_fmac_f32_e32 v127, v126, v126
	v_and_b32_e32 v126, 0xffff0000, v132
	v_fmac_f32_e32 v127, v126, v126
	v_lshlrev_b32_e32 v126, 16, v133
	v_fmac_f32_e32 v127, v126, v126
	v_and_b32_e32 v126, 0xffff0000, v133
	v_fmac_f32_e32 v127, v126, v126
	v_add_f32_e32 v126, v152, v127
	v_mov_b32_e32 v127, v126
	s_nop 1
	v_permlane16_swap_b32_e32 v127, v126
	global_store_dwordx4 v[210:211], v[130:133], off offset:256
	s_waitcnt lgkmcnt(0)
	v_add_f32_e32 v128, v126, v127
	v_mov_b32_e32 v129, v128
	s_nop 1
	v_permlane32_swap_b32_e32 v129, v128
	v_lshl_add_u64 v[126:127], v[212:213], 3, s[12:13]
	s_and_saveexec_b64 s[4:5], vcc
	s_cbranch_execz .LBB0_1101
	s_waitcnt lgkmcnt(0)
	v_add_f32_e32 v128, v128, v129
	v_mul_f32_e32 v128, 0x48800000, v128
	v_cvt_u32_f32_e32 v128, v128
	v_mov_b32_e32 v129, v0
	global_atomic_add_x2 v[126:127], v[128:129], off
.LBB0_1101:
	s_or_b64 exec, exec, s[4:5]
	v_lshlrev_b32_e32 v128, 16, v182
	s_waitcnt lgkmcnt(0)
	v_and_b32_e32 v129, 0xffff0000, v182
	v_pk_add_f32 v[114:115], v[114:115], v[128:129]
	v_lshlrev_b32_e32 v128, 16, v183
	v_and_b32_e32 v129, 0xffff0000, v183
	v_pk_add_f32 v[116:117], v[116:117], v[128:129]
	v_cvt_pk_bf16_f32 v114, v114, v115
	v_cvt_pk_bf16_f32 v115, v116, v117
	v_lshlrev_b32_e32 v116, 16, v184
	v_and_b32_e32 v117, 0xffff0000, v184
	v_pk_add_f32 v[106:107], v[106:107], v[116:117]
	s_mov_b64 s[4:5], 0x8000
	v_cvt_pk_bf16_f32 v116, v106, v107
	v_lshlrev_b32_e32 v106, 16, v185
	v_and_b32_e32 v107, 0xffff0000, v185
	v_pk_add_f32 v[106:107], v[108:109], v[106:107]
	s_nop 0
	v_cvt_pk_bf16_f32 v117, v106, v107
	v_and_b32_e32 v107, 0xffff0000, v114
	v_lshlrev_b32_e32 v106, 16, v114
	v_mul_f32_e32 v108, v107, v107
	v_fmac_f32_e32 v108, v106, v106
	v_lshlrev_b32_e32 v106, 16, v115
	v_fmac_f32_e32 v108, v106, v106
	v_and_b32_e32 v106, 0xffff0000, v115
	v_fmac_f32_e32 v108, v106, v106
	v_lshlrev_b32_e32 v106, 16, v116
	v_fmac_f32_e32 v108, v106, v106
	v_and_b32_e32 v106, 0xffff0000, v116
	v_fmac_f32_e32 v108, v106, v106
	v_lshlrev_b32_e32 v106, 16, v117
	v_fmac_f32_e32 v108, v106, v106
	v_and_b32_e32 v106, 0xffff0000, v117
	v_fmac_f32_e32 v108, v106, v106
	v_lshlrev_b32_e32 v106, 16, v178
	v_and_b32_e32 v107, 0xffff0000, v178
	v_pk_add_f32 v[102:103], v[102:103], v[106:107]
	v_lshlrev_b32_e32 v106, 16, v179
	v_and_b32_e32 v107, 0xffff0000, v179
	v_pk_add_f32 v[104:105], v[104:105], v[106:107]
	v_cvt_pk_bf16_f32 v102, v102, v103
	v_cvt_pk_bf16_f32 v103, v104, v105
	v_lshlrev_b32_e32 v104, 16, v180
	v_and_b32_e32 v105, 0xffff0000, v180
	v_pk_add_f32 v[98:99], v[98:99], v[104:105]
	s_nop 0
	v_cvt_pk_bf16_f32 v104, v98, v99
	v_lshlrev_b32_e32 v98, 16, v181
	v_and_b32_e32 v99, 0xffff0000, v181
	v_pk_add_f32 v[98:99], v[100:101], v[98:99]
	v_lshl_add_u64 v[100:101], v[210:211], 0, s[4:5]
	v_cvt_pk_bf16_f32 v105, v98, v99
	v_and_b32_e32 v99, 0xffff0000, v102
	v_lshlrev_b32_e32 v98, 16, v102
	v_mul_f32_e32 v99, v99, v99
	v_fmac_f32_e32 v99, v98, v98
	v_lshlrev_b32_e32 v98, 16, v103
	v_fmac_f32_e32 v99, v98, v98
	v_and_b32_e32 v98, 0xffff0000, v103
	v_fmac_f32_e32 v99, v98, v98
	v_lshlrev_b32_e32 v98, 16, v104
	v_fmac_f32_e32 v99, v98, v98
	v_and_b32_e32 v98, 0xffff0000, v104
	v_fmac_f32_e32 v99, v98, v98
	v_lshlrev_b32_e32 v98, 16, v105
	v_fmac_f32_e32 v99, v98, v98
	v_and_b32_e32 v98, 0xffff0000, v105
	v_fmac_f32_e32 v99, v98, v98
	v_add_f32_e32 v98, v108, v99
	v_mov_b32_e32 v99, v98
	s_nop 1
	v_permlane16_swap_b32_e32 v99, v98
	s_mov_b64 s[4:5], 0x8100
	v_lshl_add_u64 v[106:107], v[210:211], 0, s[4:5]
	global_store_dwordx4 v[100:101], v[114:117], off
	global_store_dwordx4 v[106:107], v[102:105], off
	s_waitcnt lgkmcnt(0)
	v_add_f32_e32 v98, v98, v99
	v_mov_b32_e32 v99, v98
	s_nop 1
	v_permlane32_swap_b32_e32 v99, v98
	s_and_saveexec_b64 s[4:5], vcc
	s_cbranch_execz .LBB0_1103
	s_waitcnt lgkmcnt(0)
	v_add_f32_e32 v98, v98, v99
	v_mul_f32_e32 v98, 0x48800000, v98
	v_cvt_u32_f32_e32 v98, v98
	v_mov_b32_e32 v99, v0
	global_atomic_add_x2 v[126:127], v[98:99], off offset:128
.LBB0_1103:
	s_or_b64 exec, exec, s[4:5]
	v_lshlrev_b32_e32 v98, 16, v174
	s_waitcnt lgkmcnt(0)
	v_and_b32_e32 v99, 0xffff0000, v174
	v_pk_add_f32 v[94:95], v[94:95], v[98:99]
	v_lshlrev_b32_e32 v98, 16, v175
	v_and_b32_e32 v99, 0xffff0000, v175
	v_pk_add_f32 v[96:97], v[96:97], v[98:99]
	v_cvt_pk_bf16_f32 v94, v94, v95
	v_cvt_pk_bf16_f32 v95, v96, v97
	v_lshlrev_b32_e32 v96, 16, v176
	v_and_b32_e32 v97, 0xffff0000, v176
	v_pk_add_f32 v[90:91], v[90:91], v[96:97]
	s_mov_b64 s[4:5], 0x10100
	v_cvt_pk_bf16_f32 v96, v90, v91
	v_lshlrev_b32_e32 v90, 16, v177
	v_and_b32_e32 v91, 0xffff0000, v177
	v_pk_add_f32 v[90:91], v[92:93], v[90:91]
	s_nop 0
	v_cvt_pk_bf16_f32 v97, v90, v91
	v_and_b32_e32 v91, 0xffff0000, v94
	v_lshlrev_b32_e32 v90, 16, v94
	v_mul_f32_e32 v92, v91, v91
	v_fmac_f32_e32 v92, v90, v90
	v_lshlrev_b32_e32 v90, 16, v95
	v_fmac_f32_e32 v92, v90, v90
	v_and_b32_e32 v90, 0xffff0000, v95
	v_fmac_f32_e32 v92, v90, v90
	v_lshlrev_b32_e32 v90, 16, v96
	v_fmac_f32_e32 v92, v90, v90
	v_and_b32_e32 v90, 0xffff0000, v96
	v_fmac_f32_e32 v92, v90, v90
	v_lshlrev_b32_e32 v90, 16, v97
	v_fmac_f32_e32 v92, v90, v90
	v_and_b32_e32 v90, 0xffff0000, v97
	v_fmac_f32_e32 v92, v90, v90
	v_lshlrev_b32_e32 v90, 16, v170
	v_and_b32_e32 v91, 0xffff0000, v170
	v_pk_add_f32 v[86:87], v[86:87], v[90:91]
	v_lshlrev_b32_e32 v90, 16, v171
	v_and_b32_e32 v91, 0xffff0000, v171
	v_pk_add_f32 v[88:89], v[88:89], v[90:91]
	v_cvt_pk_bf16_f32 v86, v86, v87
	v_cvt_pk_bf16_f32 v87, v88, v89
	v_lshlrev_b32_e32 v88, 16, v172
	v_and_b32_e32 v89, 0xffff0000, v172
	v_pk_add_f32 v[82:83], v[82:83], v[88:89]
	v_lshl_add_u64 v[90:91], v[210:211], 0, s[4:5]
	v_cvt_pk_bf16_f32 v88, v82, v83
	v_lshlrev_b32_e32 v82, 16, v173
	v_and_b32_e32 v83, 0xffff0000, v173
	v_pk_add_f32 v[82:83], v[84:85], v[82:83]
	v_lshl_add_u64 v[84:85], v[210:211], 0, s[90:91]
	v_cvt_pk_bf16_f32 v89, v82, v83
	v_and_b32_e32 v83, 0xffff0000, v86
	v_lshlrev_b32_e32 v82, 16, v86
	v_mul_f32_e32 v83, v83, v83
	v_fmac_f32_e32 v83, v82, v82
	v_lshlrev_b32_e32 v82, 16, v87
	v_fmac_f32_e32 v83, v82, v82
	v_and_b32_e32 v82, 0xffff0000, v87
	v_fmac_f32_e32 v83, v82, v82
	v_lshlrev_b32_e32 v82, 16, v88
	v_fmac_f32_e32 v83, v82, v82
	v_and_b32_e32 v82, 0xffff0000, v88
	v_fmac_f32_e32 v83, v82, v82
	v_lshlrev_b32_e32 v82, 16, v89
	v_fmac_f32_e32 v83, v82, v82
	v_and_b32_e32 v82, 0xffff0000, v89
	v_fmac_f32_e32 v83, v82, v82
	v_add_f32_e32 v82, v92, v83
	v_mov_b32_e32 v83, v82
	s_nop 1
	v_permlane16_swap_b32_e32 v83, v82
	global_store_dwordx4 v[84:85], v[94:97], off
	global_store_dwordx4 v[90:91], v[86:89], off
	s_waitcnt lgkmcnt(0)
	v_add_f32_e32 v82, v82, v83
	v_mov_b32_e32 v83, v82
	s_nop 1
	v_permlane32_swap_b32_e32 v83, v82
	s_and_saveexec_b64 s[4:5], vcc
	s_cbranch_execz .LBB0_1105
	s_waitcnt lgkmcnt(0)
	v_add_f32_e32 v82, v82, v83
	v_mul_f32_e32 v82, 0x48800000, v82
	v_cvt_u32_f32_e32 v82, v82
	v_mov_b32_e32 v83, v0
	global_atomic_add_x2 v[126:127], v[82:83], off offset:256
.LBB0_1105:
	s_or_b64 exec, exec, s[4:5]
	v_lshlrev_b32_e32 v82, 16, v166
	s_waitcnt lgkmcnt(0)
	v_and_b32_e32 v83, 0xffff0000, v166
	v_pk_add_f32 v[78:79], v[78:79], v[82:83]
	v_lshlrev_b32_e32 v82, 16, v167
	v_and_b32_e32 v83, 0xffff0000, v167
	v_pk_add_f32 v[80:81], v[80:81], v[82:83]
	v_cvt_pk_bf16_f32 v78, v78, v79
	v_cvt_pk_bf16_f32 v79, v80, v81
	v_lshlrev_b32_e32 v80, 16, v168
	v_and_b32_e32 v81, 0xffff0000, v168
	v_pk_add_f32 v[74:75], v[74:75], v[80:81]
	s_mov_b64 s[4:5], 0x18000
	v_cvt_pk_bf16_f32 v80, v74, v75
	v_lshlrev_b32_e32 v74, 16, v169
	v_and_b32_e32 v75, 0xffff0000, v169
	v_pk_add_f32 v[74:75], v[76:77], v[74:75]
	s_nop 0
	v_cvt_pk_bf16_f32 v81, v74, v75
	v_and_b32_e32 v75, 0xffff0000, v78
	v_lshlrev_b32_e32 v74, 16, v78
	v_mul_f32_e32 v76, v75, v75
	v_fmac_f32_e32 v76, v74, v74
	v_lshlrev_b32_e32 v74, 16, v79
	v_fmac_f32_e32 v76, v74, v74
	v_and_b32_e32 v74, 0xffff0000, v79
	v_fmac_f32_e32 v76, v74, v74
	v_lshlrev_b32_e32 v74, 16, v80
	v_fmac_f32_e32 v76, v74, v74
	v_and_b32_e32 v74, 0xffff0000, v80
	v_fmac_f32_e32 v76, v74, v74
	v_lshlrev_b32_e32 v74, 16, v81
	v_fmac_f32_e32 v76, v74, v74
	v_and_b32_e32 v74, 0xffff0000, v81
	v_fmac_f32_e32 v76, v74, v74
	v_lshlrev_b32_e32 v74, 16, v162
	v_and_b32_e32 v75, 0xffff0000, v162
	v_pk_add_f32 v[70:71], v[70:71], v[74:75]
	v_lshlrev_b32_e32 v74, 16, v163
	v_and_b32_e32 v75, 0xffff0000, v163
	v_pk_add_f32 v[72:73], v[72:73], v[74:75]
	v_cvt_pk_bf16_f32 v70, v70, v71
	v_cvt_pk_bf16_f32 v71, v72, v73
	v_lshlrev_b32_e32 v72, 16, v164
	v_and_b32_e32 v73, 0xffff0000, v164
	v_pk_add_f32 v[66:67], v[66:67], v[72:73]
	s_nop 0
	v_cvt_pk_bf16_f32 v72, v66, v67
	v_lshlrev_b32_e32 v66, 16, v165
	v_and_b32_e32 v67, 0xffff0000, v165
	v_pk_add_f32 v[66:67], v[68:69], v[66:67]
	v_lshl_add_u64 v[68:69], v[210:211], 0, s[4:5]
	v_cvt_pk_bf16_f32 v73, v66, v67
	v_and_b32_e32 v67, 0xffff0000, v70
	v_lshlrev_b32_e32 v66, 16, v70
	v_mul_f32_e32 v67, v67, v67
	v_fmac_f32_e32 v67, v66, v66
	v_lshlrev_b32_e32 v66, 16, v71
	v_fmac_f32_e32 v67, v66, v66
	v_and_b32_e32 v66, 0xffff0000, v71
	v_fmac_f32_e32 v67, v66, v66
	v_lshlrev_b32_e32 v66, 16, v72
	v_fmac_f32_e32 v67, v66, v66
	v_and_b32_e32 v66, 0xffff0000, v72
	v_fmac_f32_e32 v67, v66, v66
	v_lshlrev_b32_e32 v66, 16, v73
	v_fmac_f32_e32 v67, v66, v66
	v_and_b32_e32 v66, 0xffff0000, v73
	v_fmac_f32_e32 v67, v66, v66
	v_add_f32_e32 v66, v76, v67
	v_mov_b32_e32 v67, v66
	s_nop 1
	v_permlane16_swap_b32_e32 v67, v66
	s_mov_b64 s[4:5], 0x18100
	v_lshl_add_u64 v[74:75], v[210:211], 0, s[4:5]
	global_store_dwordx4 v[68:69], v[78:81], off
	global_store_dwordx4 v[74:75], v[70:73], off
	s_waitcnt lgkmcnt(0)
	v_add_f32_e32 v66, v66, v67
	v_mov_b32_e32 v67, v66
	s_nop 1
	v_permlane32_swap_b32_e32 v67, v66
	s_and_saveexec_b64 s[4:5], vcc
	s_cbranch_execz .LBB0_1107
	s_waitcnt lgkmcnt(0)
	v_add_f32_e32 v66, v66, v67
	v_mul_f32_e32 v66, 0x48800000, v66
	v_cvt_u32_f32_e32 v66, v66
	v_mov_b32_e32 v67, v0
	global_atomic_add_x2 v[126:127], v[66:67], off offset:384
.LBB0_1107:
	s_or_b64 exec, exec, s[4:5]
	v_lshlrev_b32_e32 v66, 16, v154
	s_waitcnt lgkmcnt(0)
	v_and_b32_e32 v67, 0xffff0000, v154
	v_pk_add_f32 v[62:63], v[62:63], v[66:67]
	v_lshlrev_b32_e32 v66, 16, v155
	v_and_b32_e32 v67, 0xffff0000, v155
	v_pk_add_f32 v[64:65], v[64:65], v[66:67]
	v_cvt_pk_bf16_f32 v62, v62, v63
	v_cvt_pk_bf16_f32 v63, v64, v65
	v_lshlrev_b32_e32 v64, 16, v156
	v_and_b32_e32 v65, 0xffff0000, v156
	v_pk_add_f32 v[58:59], v[58:59], v[64:65]
	s_mov_b64 s[4:5], 0x40100
	v_cvt_pk_bf16_f32 v64, v58, v59
	v_lshlrev_b32_e32 v58, 16, v157
	v_and_b32_e32 v59, 0xffff0000, v157
	v_pk_add_f32 v[58:59], v[60:61], v[58:59]
	s_nop 0
	v_cvt_pk_bf16_f32 v65, v58, v59
	v_and_b32_e32 v59, 0xffff0000, v62
	v_lshlrev_b32_e32 v58, 16, v62
	v_mul_f32_e32 v60, v59, v59
	v_fmac_f32_e32 v60, v58, v58
	v_lshlrev_b32_e32 v58, 16, v63
	v_fmac_f32_e32 v60, v58, v58
	v_and_b32_e32 v58, 0xffff0000, v63
	v_fmac_f32_e32 v60, v58, v58
	v_lshlrev_b32_e32 v58, 16, v64
	v_fmac_f32_e32 v60, v58, v58
	v_and_b32_e32 v58, 0xffff0000, v64
	v_fmac_f32_e32 v60, v58, v58
	v_lshlrev_b32_e32 v58, 16, v65
	v_fmac_f32_e32 v60, v58, v58
	v_and_b32_e32 v58, 0xffff0000, v65
	v_fmac_f32_e32 v60, v58, v58
	v_lshlrev_b32_e32 v58, 16, v146
	v_and_b32_e32 v59, 0xffff0000, v146
	v_pk_add_f32 v[54:55], v[54:55], v[58:59]
	v_lshlrev_b32_e32 v58, 16, v147
	v_and_b32_e32 v59, 0xffff0000, v147
	v_pk_add_f32 v[56:57], v[56:57], v[58:59]
	v_cvt_pk_bf16_f32 v54, v54, v55
	v_cvt_pk_bf16_f32 v55, v56, v57
	v_lshlrev_b32_e32 v56, 16, v148
	v_and_b32_e32 v57, 0xffff0000, v148
	v_pk_add_f32 v[50:51], v[50:51], v[56:57]
	v_lshl_add_u64 v[58:59], v[210:211], 0, s[4:5]
	v_cvt_pk_bf16_f32 v56, v50, v51
	v_lshlrev_b32_e32 v50, 16, v149
	v_and_b32_e32 v51, 0xffff0000, v149
	v_pk_add_f32 v[50:51], v[52:53], v[50:51]
	v_lshl_add_u64 v[52:53], v[210:211], 0, s[72:73]
	v_cvt_pk_bf16_f32 v57, v50, v51
	v_and_b32_e32 v51, 0xffff0000, v54
	v_lshlrev_b32_e32 v50, 16, v54
	v_mul_f32_e32 v51, v51, v51
	v_fmac_f32_e32 v51, v50, v50
	v_lshlrev_b32_e32 v50, 16, v55
	v_fmac_f32_e32 v51, v50, v50
	v_and_b32_e32 v50, 0xffff0000, v55
	v_fmac_f32_e32 v51, v50, v50
	v_lshlrev_b32_e32 v50, 16, v56
	v_fmac_f32_e32 v51, v50, v50
	v_and_b32_e32 v50, 0xffff0000, v56
	v_fmac_f32_e32 v51, v50, v50
	v_lshlrev_b32_e32 v50, 16, v57
	v_fmac_f32_e32 v51, v50, v50
	v_and_b32_e32 v50, 0xffff0000, v57
	v_fmac_f32_e32 v51, v50, v50
	v_add_f32_e32 v50, v60, v51
	v_mov_b32_e32 v51, v50
	s_nop 1
	v_permlane16_swap_b32_e32 v51, v50
	global_store_dwordx4 v[52:53], v[62:65], off
	global_store_dwordx4 v[58:59], v[54:57], off
	s_waitcnt lgkmcnt(0)
	v_add_f32_e32 v50, v50, v51
	v_mov_b32_e32 v51, v50
	s_nop 1
	v_permlane32_swap_b32_e32 v51, v50
	s_and_saveexec_b64 s[4:5], vcc
	s_cbranch_execz .LBB0_1109
	s_waitcnt lgkmcnt(0)
	v_add_f32_e32 v50, v50, v51
	v_mul_f32_e32 v50, 0x48800000, v50
	v_cvt_u32_f32_e32 v50, v50
	v_mov_b32_e32 v51, v0
	global_atomic_add_x2 v[126:127], v[50:51], off offset:1024
.LBB0_1109:
	s_or_b64 exec, exec, s[4:5]
	v_lshlrev_b32_e32 v50, 16, v142
	s_waitcnt lgkmcnt(0)
	v_and_b32_e32 v51, 0xffff0000, v142
	v_pk_add_f32 v[46:47], v[46:47], v[50:51]
	v_lshlrev_b32_e32 v50, 16, v143
	v_and_b32_e32 v51, 0xffff0000, v143
	v_pk_add_f32 v[48:49], v[48:49], v[50:51]
	v_cvt_pk_bf16_f32 v46, v46, v47
	v_cvt_pk_bf16_f32 v47, v48, v49
	v_lshlrev_b32_e32 v48, 16, v144
	v_and_b32_e32 v49, 0xffff0000, v144
	v_pk_add_f32 v[42:43], v[42:43], v[48:49]
	s_mov_b64 s[4:5], 0x48000
	v_cvt_pk_bf16_f32 v48, v42, v43
	v_lshlrev_b32_e32 v42, 16, v145
	v_and_b32_e32 v43, 0xffff0000, v145
	v_pk_add_f32 v[42:43], v[44:45], v[42:43]
	s_nop 0
	v_cvt_pk_bf16_f32 v49, v42, v43
	v_and_b32_e32 v43, 0xffff0000, v46
	v_lshlrev_b32_e32 v42, 16, v46
	v_mul_f32_e32 v44, v43, v43
	v_fmac_f32_e32 v44, v42, v42
	v_lshlrev_b32_e32 v42, 16, v47
	v_fmac_f32_e32 v44, v42, v42
	v_and_b32_e32 v42, 0xffff0000, v47
	v_fmac_f32_e32 v44, v42, v42
	v_lshlrev_b32_e32 v42, 16, v48
	v_fmac_f32_e32 v44, v42, v42
	v_and_b32_e32 v42, 0xffff0000, v48
	v_fmac_f32_e32 v44, v42, v42
	v_lshlrev_b32_e32 v42, 16, v49
	v_fmac_f32_e32 v44, v42, v42
	v_and_b32_e32 v42, 0xffff0000, v49
	v_fmac_f32_e32 v44, v42, v42
	v_lshlrev_b32_e32 v42, 16, v138
	v_and_b32_e32 v43, 0xffff0000, v138
	v_pk_add_f32 v[38:39], v[38:39], v[42:43]
	v_lshlrev_b32_e32 v42, 16, v139
	v_and_b32_e32 v43, 0xffff0000, v139
	v_pk_add_f32 v[40:41], v[40:41], v[42:43]
	v_cvt_pk_bf16_f32 v38, v38, v39
	v_cvt_pk_bf16_f32 v39, v40, v41
	v_lshlrev_b32_e32 v40, 16, v140
	v_and_b32_e32 v41, 0xffff0000, v140
	v_pk_add_f32 v[34:35], v[34:35], v[40:41]
	s_nop 0
	v_cvt_pk_bf16_f32 v40, v34, v35
	v_lshlrev_b32_e32 v34, 16, v141
	v_and_b32_e32 v35, 0xffff0000, v141
	v_pk_add_f32 v[34:35], v[36:37], v[34:35]
	v_lshl_add_u64 v[36:37], v[210:211], 0, s[4:5]
	v_cvt_pk_bf16_f32 v41, v34, v35
	v_and_b32_e32 v35, 0xffff0000, v38
	v_lshlrev_b32_e32 v34, 16, v38
	v_mul_f32_e32 v35, v35, v35
	v_fmac_f32_e32 v35, v34, v34
	v_lshlrev_b32_e32 v34, 16, v39
	v_fmac_f32_e32 v35, v34, v34
	v_and_b32_e32 v34, 0xffff0000, v39
	v_fmac_f32_e32 v35, v34, v34
	v_lshlrev_b32_e32 v34, 16, v40
	v_fmac_f32_e32 v35, v34, v34
	v_and_b32_e32 v34, 0xffff0000, v40
	v_fmac_f32_e32 v35, v34, v34
	v_lshlrev_b32_e32 v34, 16, v41
	v_fmac_f32_e32 v35, v34, v34
	v_and_b32_e32 v34, 0xffff0000, v41
	v_fmac_f32_e32 v35, v34, v34
	v_add_f32_e32 v34, v44, v35
	v_mov_b32_e32 v35, v34
	s_nop 1
	v_permlane16_swap_b32_e32 v35, v34
	s_mov_b64 s[4:5], 0x48100
	v_lshl_add_u64 v[42:43], v[210:211], 0, s[4:5]
	global_store_dwordx4 v[36:37], v[46:49], off
	global_store_dwordx4 v[42:43], v[38:41], off
	s_waitcnt lgkmcnt(0)
	v_add_f32_e32 v34, v34, v35
	v_mov_b32_e32 v35, v34
	s_nop 1
	v_permlane32_swap_b32_e32 v35, v34
	s_and_saveexec_b64 s[4:5], vcc
	s_cbranch_execz .LBB0_1111
	s_waitcnt lgkmcnt(0)
	v_add_f32_e32 v34, v34, v35
	v_mul_f32_e32 v34, 0x48800000, v34
	v_cvt_u32_f32_e32 v34, v34
	v_mov_b32_e32 v35, v0
	global_atomic_add_x2 v[126:127], v[34:35], off offset:1152
.LBB0_1111:
	s_or_b64 exec, exec, s[4:5]
	s_waitcnt vmcnt(15)
	v_lshlrev_b32_e32 v34, 16, v134
	s_waitcnt lgkmcnt(0)
	v_and_b32_e32 v35, 0xffff0000, v134
	v_pk_add_f32 v[30:31], v[30:31], v[34:35]
	v_lshlrev_b32_e32 v34, 16, v135
	v_and_b32_e32 v35, 0xffff0000, v135
	v_pk_add_f32 v[32:33], v[32:33], v[34:35]
	v_cvt_pk_bf16_f32 v30, v30, v31
	v_cvt_pk_bf16_f32 v31, v32, v33
	v_lshlrev_b32_e32 v32, 16, v136
	v_and_b32_e32 v33, 0xffff0000, v136
	v_pk_add_f32 v[26:27], v[26:27], v[32:33]
	s_mov_b64 s[4:5], 0x50000
	v_cvt_pk_bf16_f32 v32, v26, v27
	v_lshlrev_b32_e32 v26, 16, v137
	v_and_b32_e32 v27, 0xffff0000, v137
	v_pk_add_f32 v[26:27], v[28:29], v[26:27]
	s_nop 0
	v_cvt_pk_bf16_f32 v33, v26, v27
	v_and_b32_e32 v27, 0xffff0000, v30
	v_lshlrev_b32_e32 v26, 16, v30
	v_mul_f32_e32 v28, v27, v27
	v_fmac_f32_e32 v28, v26, v26
	v_lshlrev_b32_e32 v26, 16, v31
	v_fmac_f32_e32 v28, v26, v26
	v_and_b32_e32 v26, 0xffff0000, v31
	v_fmac_f32_e32 v28, v26, v26
	v_lshlrev_b32_e32 v26, 16, v32
	v_fmac_f32_e32 v28, v26, v26
	v_and_b32_e32 v26, 0xffff0000, v32
	v_fmac_f32_e32 v28, v26, v26
	v_lshlrev_b32_e32 v26, 16, v33
	v_fmac_f32_e32 v28, v26, v26
	v_and_b32_e32 v26, 0xffff0000, v33
	v_fmac_f32_e32 v28, v26, v26
	s_waitcnt vmcnt(14)
	v_lshlrev_b32_e32 v26, 16, v122
	v_and_b32_e32 v27, 0xffff0000, v122
	v_pk_add_f32 v[22:23], v[22:23], v[26:27]
	v_lshlrev_b32_e32 v26, 16, v123
	v_and_b32_e32 v27, 0xffff0000, v123
	v_pk_add_f32 v[24:25], v[24:25], v[26:27]
	v_cvt_pk_bf16_f32 v22, v22, v23
	v_cvt_pk_bf16_f32 v23, v24, v25
	v_lshlrev_b32_e32 v24, 16, v124
	v_and_b32_e32 v25, 0xffff0000, v124
	v_pk_add_f32 v[18:19], v[18:19], v[24:25]
	s_nop 0
	v_cvt_pk_bf16_f32 v24, v18, v19
	v_lshlrev_b32_e32 v18, 16, v125
	v_and_b32_e32 v19, 0xffff0000, v125
	v_pk_add_f32 v[18:19], v[20:21], v[18:19]
	v_lshl_add_u64 v[20:21], v[210:211], 0, s[4:5]
	v_cvt_pk_bf16_f32 v25, v18, v19
	v_and_b32_e32 v19, 0xffff0000, v22
	v_lshlrev_b32_e32 v18, 16, v22
	v_mul_f32_e32 v19, v19, v19
	v_fmac_f32_e32 v19, v18, v18
	v_lshlrev_b32_e32 v18, 16, v23
	v_fmac_f32_e32 v19, v18, v18
	v_and_b32_e32 v18, 0xffff0000, v23
	v_fmac_f32_e32 v19, v18, v18
	v_lshlrev_b32_e32 v18, 16, v24
	v_fmac_f32_e32 v19, v18, v18
	v_and_b32_e32 v18, 0xffff0000, v24
	v_fmac_f32_e32 v19, v18, v18
	v_lshlrev_b32_e32 v18, 16, v25
	v_fmac_f32_e32 v19, v18, v18
	v_and_b32_e32 v18, 0xffff0000, v25
	v_fmac_f32_e32 v19, v18, v18
	v_add_f32_e32 v18, v28, v19
	v_mov_b32_e32 v19, v18
	s_nop 1
	v_permlane16_swap_b32_e32 v19, v18
	s_mov_b64 s[4:5], 0x50100
	v_lshl_add_u64 v[26:27], v[210:211], 0, s[4:5]
	global_store_dwordx4 v[20:21], v[30:33], off
	global_store_dwordx4 v[26:27], v[22:25], off
	s_waitcnt lgkmcnt(0)
	v_add_f32_e32 v18, v18, v19
	v_mov_b32_e32 v19, v18
	s_nop 1
	v_permlane32_swap_b32_e32 v19, v18
	s_and_saveexec_b64 s[4:5], vcc
	s_cbranch_execz .LBB0_1113
	s_waitcnt lgkmcnt(0)
	v_add_f32_e32 v18, v18, v19
	v_mul_f32_e32 v18, 0x48800000, v18
	v_cvt_u32_f32_e32 v18, v18
	v_mov_b32_e32 v19, v0
	global_atomic_add_x2 v[126:127], v[18:19], off offset:1280
.LBB0_1113:
	s_or_b64 exec, exec, s[4:5]
	s_waitcnt vmcnt(15)
	v_lshlrev_b32_e32 v18, 16, v118
	s_waitcnt lgkmcnt(0)
	v_and_b32_e32 v19, 0xffff0000, v118
	v_pk_add_f32 v[14:15], v[14:15], v[18:19]
	v_lshlrev_b32_e32 v18, 16, v119
	v_and_b32_e32 v19, 0xffff0000, v119
	v_pk_add_f32 v[16:17], v[16:17], v[18:19]
	v_cvt_pk_bf16_f32 v14, v14, v15
	v_cvt_pk_bf16_f32 v15, v16, v17
	v_lshlrev_b32_e32 v16, 16, v120
	v_and_b32_e32 v17, 0xffff0000, v120
	v_pk_add_f32 v[10:11], v[10:11], v[16:17]
	s_mov_b64 s[4:5], 0x58000
	v_cvt_pk_bf16_f32 v16, v10, v11
	v_lshlrev_b32_e32 v10, 16, v121
	v_and_b32_e32 v11, 0xffff0000, v121
	v_pk_add_f32 v[10:11], v[12:13], v[10:11]
	s_nop 0
	v_cvt_pk_bf16_f32 v17, v10, v11
	v_and_b32_e32 v11, 0xffff0000, v14
	v_lshlrev_b32_e32 v10, 16, v14
	v_mul_f32_e32 v12, v11, v11
	v_fmac_f32_e32 v12, v10, v10
	v_lshlrev_b32_e32 v10, 16, v15
	v_fmac_f32_e32 v12, v10, v10
	v_and_b32_e32 v10, 0xffff0000, v15
	v_fmac_f32_e32 v12, v10, v10
	v_lshlrev_b32_e32 v10, 16, v16
	v_fmac_f32_e32 v12, v10, v10
	v_and_b32_e32 v10, 0xffff0000, v16
	v_fmac_f32_e32 v12, v10, v10
	v_lshlrev_b32_e32 v10, 16, v17
	v_fmac_f32_e32 v12, v10, v10
	v_and_b32_e32 v10, 0xffff0000, v17
	v_fmac_f32_e32 v12, v10, v10
	s_waitcnt vmcnt(14)
	v_lshlrev_b32_e32 v10, 16, v110
	v_and_b32_e32 v11, 0xffff0000, v110
	v_pk_add_f32 v[6:7], v[6:7], v[10:11]
	v_lshlrev_b32_e32 v10, 16, v111
	v_and_b32_e32 v11, 0xffff0000, v111
	v_pk_add_f32 v[8:9], v[8:9], v[10:11]
	v_cvt_pk_bf16_f32 v6, v6, v7
	v_cvt_pk_bf16_f32 v7, v8, v9
	v_lshlrev_b32_e32 v8, 16, v112
	v_and_b32_e32 v9, 0xffff0000, v112
	v_pk_add_f32 v[2:3], v[2:3], v[8:9]
	s_nop 0
	v_cvt_pk_bf16_f32 v8, v2, v3
	v_lshlrev_b32_e32 v2, 16, v113
	v_and_b32_e32 v3, 0xffff0000, v113
	v_pk_add_f32 v[2:3], v[4:5], v[2:3]
	v_lshl_add_u64 v[4:5], v[210:211], 0, s[4:5]
	v_cvt_pk_bf16_f32 v9, v2, v3
	v_and_b32_e32 v3, 0xffff0000, v6
	v_lshlrev_b32_e32 v2, 16, v6
	v_mul_f32_e32 v3, v3, v3
	v_fmac_f32_e32 v3, v2, v2
	v_lshlrev_b32_e32 v2, 16, v7
	v_fmac_f32_e32 v3, v2, v2
	v_and_b32_e32 v2, 0xffff0000, v7
	v_fmac_f32_e32 v3, v2, v2
	v_lshlrev_b32_e32 v2, 16, v8
	v_fmac_f32_e32 v3, v2, v2
	v_and_b32_e32 v2, 0xffff0000, v8
	v_fmac_f32_e32 v3, v2, v2
	v_lshlrev_b32_e32 v2, 16, v9
	v_fmac_f32_e32 v3, v2, v2
	v_and_b32_e32 v2, 0xffff0000, v9
	v_fmac_f32_e32 v3, v2, v2
	v_add_f32_e32 v2, v12, v3
	v_mov_b32_e32 v3, v2
	s_nop 1
	v_permlane16_swap_b32_e32 v3, v2
	s_mov_b64 s[4:5], 0x58100
	v_lshl_add_u64 v[10:11], v[210:211], 0, s[4:5]
	global_store_dwordx4 v[4:5], v[14:17], off
	global_store_dwordx4 v[10:11], v[6:9], off
	s_waitcnt lgkmcnt(0)
	v_add_f32_e32 v2, v2, v3
	v_mov_b32_e32 v3, v2
	s_nop 1
	v_permlane32_swap_b32_e32 v3, v2
	s_and_saveexec_b64 s[4:5], vcc
	s_cbranch_execz .LBB0_1115
	s_waitcnt lgkmcnt(0)
	v_add_f32_e32 v2, v2, v3
	v_mul_f32_e32 v2, 0x48800000, v2
	v_cvt_u32_f32_e32 v2, v2
	v_mov_b32_e32 v3, v0
	global_atomic_add_x2 v[126:127], v[2:3], off offset:1408

.LBB0_1266:
	v_mov_b32_e32 v110, v218
	s_lshl_b32 s18, s49, 8
	s_add_i32 s18, s18, s39
	v_and_b32_e32 v196, 15, v110
	v_bfe_u32 v197, v110, 4, 2
	v_or_b32_e32 v212, s18, v196
	s_lshl_b32 s18, s48, 8
	v_lshl_or_b32 v110, v197, 3, s18
	v_ashrrev_i32_e32 v213, 31, v212
	v_or_b32_e32 v110, s40, v110
	v_lshlrev_b64 v[112:113], 11, v[212:213]
	v_lshl_add_u64 v[112:113], s[10:11], 0, v[112:113]
	v_ashrrev_i32_e32 v111, 31, v110
	v_lshl_add_u64 v[210:211], v[110:111], 1, v[112:113]
	global_load_dwordx4 v[228:231], v[210:211], off
	global_load_dwordx4 v[186:189], v[210:211], off offset:256
	v_add_co_u32_e32 v110, vcc, s75, v210
	s_mov_b32 s18, 0x58000
	s_nop 0
	v_addc_co_u32_e32 v111, vcc, 0, v211, vcc
	global_load_dwordx4 v[182:185], v[110:111], off
	global_load_dwordx4 v[178:181], v[110:111], off offset:256
	v_add_co_u32_e32 v110, vcc, s71, v210
	v_lshlrev_b32_e32 v198, 6, v197
	s_nop 0
	v_addc_co_u32_e32 v111, vcc, 0, v211, vcc
	global_load_dwordx4 v[174:177], v[110:111], off
	global_load_dwordx4 v[170:173], v[110:111], off offset:256
	v_add_co_u32_e32 v110, vcc, s74, v210
	v_lshlrev_b32_e32 v196, 2, v196
	s_nop 0
	v_addc_co_u32_e32 v111, vcc, 0, v211, vcc
	global_load_dwordx4 v[166:169], v[110:111], off
	global_load_dwordx4 v[162:165], v[110:111], off offset:256
	v_add_co_u32_e32 v110, vcc, s87, v210
	v_bitop3_b32 v216, v198, 64, v196 bitop3:0x36
	s_nop 0
	v_addc_co_u32_e32 v111, vcc, 0, v211, vcc
	global_load_dwordx4 v[154:157], v[110:111], off
	global_load_dwordx4 v[146:149], v[110:111], off offset:256
	v_add_co_u32_e32 v110, vcc, s92, v210
	v_bitop3_b32 v215, v198, s82, v196 bitop3:0x36
	s_nop 0
	v_addc_co_u32_e32 v111, vcc, 0, v211, vcc
	global_load_dwordx4 v[142:145], v[110:111], off
	global_load_dwordx4 v[138:141], v[110:111], off offset:256
	v_add_co_u32_e32 v110, vcc, s93, v210
	s_waitcnt vmcnt(0)
	v_lshlrev_b32_e32 v196, 16, v228
	v_addc_co_u32_e32 v111, vcc, 0, v211, vcc
	global_load_dwordx4 v[134:137], v[110:111], off
	global_load_dwordx4 v[122:125], v[110:111], off offset:256
	v_add_co_u32_e32 v110, vcc, s18, v210
	s_nop 1
	v_addc_co_u32_e32 v111, vcc, 0, v211, vcc
	global_load_dwordx4 v[118:121], v[110:111], off
	s_nop 0
	global_load_dwordx4 v[110:113], v[110:111], off offset:256
	v_cmp_eq_u32_e32 vcc, 0, v197
	v_and_b32_e32 v197, 0xffff0000, v228
	v_pk_fma_f32 v[158:159], v[158:159], 0.5, v[196:197] op_sel_hi:[1,0,1]
	v_lshlrev_b32_e32 v196, 16, v229
	v_and_b32_e32 v197, 0xffff0000, v229
	v_pk_fma_f32 v[160:161], v[160:161], 0.5, v[196:197] op_sel_hi:[1,0,1]
	v_cvt_pk_bf16_f32 v158, v158, v159
	v_cvt_pk_bf16_f32 v159, v160, v161
	v_lshlrev_b32_e32 v160, 16, v230
	v_and_b32_e32 v161, 0xffff0000, v230
	v_pk_fma_f32 v[150:151], v[150:151], 0.5, v[160:161] op_sel_hi:[1,0,1]
	s_nop 0
	v_cvt_pk_bf16_f32 v160, v150, v151
	v_lshlrev_b32_e32 v150, 16, v231
	v_and_b32_e32 v151, 0xffff0000, v231
	v_pk_fma_f32 v[150:151], v[152:153], 0.5, v[150:151] op_sel_hi:[1,0,1]
	s_nop 0
	v_cvt_pk_bf16_f32 v161, v150, v151
	v_and_b32_e32 v151, 0xffff0000, v158
	v_lshlrev_b32_e32 v150, 16, v158
	v_mul_f32_e32 v152, v151, v151
	v_fmac_f32_e32 v152, v150, v150
	v_lshlrev_b32_e32 v150, 16, v159
	v_fmac_f32_e32 v152, v150, v150
	v_and_b32_e32 v150, 0xffff0000, v159
	v_fmac_f32_e32 v152, v150, v150
	v_lshlrev_b32_e32 v150, 16, v160
	v_fmac_f32_e32 v152, v150, v150
	v_and_b32_e32 v150, 0xffff0000, v160
	v_fmac_f32_e32 v152, v150, v150
	v_lshlrev_b32_e32 v150, 16, v161
	v_fmac_f32_e32 v152, v150, v150
	v_and_b32_e32 v150, 0xffff0000, v161
	v_fmac_f32_e32 v152, v150, v150
	v_lshlrev_b32_e32 v150, 16, v186
	v_and_b32_e32 v151, 0xffff0000, v186
	v_pk_fma_f32 v[130:131], v[130:131], 0.5, v[150:151] op_sel_hi:[1,0,1]
	v_lshlrev_b32_e32 v150, 16, v187
	v_and_b32_e32 v151, 0xffff0000, v187
	v_pk_fma_f32 v[132:133], v[132:133], 0.5, v[150:151] op_sel_hi:[1,0,1]
	v_cvt_pk_bf16_f32 v130, v130, v131
	v_cvt_pk_bf16_f32 v131, v132, v133
	v_lshlrev_b32_e32 v132, 16, v188
	v_and_b32_e32 v133, 0xffff0000, v188
	v_pk_fma_f32 v[126:127], v[126:127], 0.5, v[132:133] op_sel_hi:[1,0,1]
	global_store_dwordx4 v[210:211], v[158:161], off
	v_cvt_pk_bf16_f32 v132, v126, v127
	v_lshlrev_b32_e32 v126, 16, v189
	v_and_b32_e32 v127, 0xffff0000, v189
	v_pk_fma_f32 v[126:127], v[128:129], 0.5, v[126:127] op_sel_hi:[1,0,1]
	s_nop 0
	v_cvt_pk_bf16_f32 v133, v126, v127
	v_and_b32_e32 v127, 0xffff0000, v130
	v_lshlrev_b32_e32 v126, 16, v130
	v_mul_f32_e32 v127, v127, v127
	v_fmac_f32_e32 v127, v126, v126
	v_lshlrev_b32_e32 v126, 16, v131
	v_fmac_f32_e32 v127, v126, v126
	v_and_b32_e32 v126, 0xffff0000, v131
	v_fmac_f32_e32 v127, v126, v126
	v_lshlrev_b32_e32 v126, 16, v132
	v_fmac_f32_e32 v127, v126, v126
	v_and_b32_e32 v126, 0xffff0000, v132
	v_fmac_f32_e32 v127, v126, v126
	v_lshlrev_b32_e32 v126, 16, v133
	v_fmac_f32_e32 v127, v126, v126
	v_and_b32_e32 v126, 0xffff0000, v133
	v_fmac_f32_e32 v127, v126, v126
	v_add_f32_e32 v126, v152, v127
	v_mov_b32_e32 v127, v126
	s_nop 1
	v_permlane16_swap_b32_e32 v127, v126
	global_store_dwordx4 v[210:211], v[130:133], off offset:256
	s_waitcnt lgkmcnt(0)
	v_add_f32_e32 v128, v126, v127
	v_mov_b32_e32 v129, v128
	s_nop 1
	v_permlane32_swap_b32_e32 v129, v128
	v_lshl_add_u64 v[126:127], v[212:213], 3, s[12:13]
	s_and_saveexec_b64 s[18:19], vcc
	s_cbranch_execz .LBB0_1268
	s_waitcnt lgkmcnt(0)
	v_add_f32_e32 v128, v128, v129
	v_mul_f32_e32 v128, 0x48800000, v128
	v_cvt_u32_f32_e32 v128, v128
	v_mov_b32_e32 v129, v0
	global_atomic_add_x2 v[126:127], v[128:129], off
.LBB0_1268:
	s_or_b64 exec, exec, s[18:19]
	v_lshlrev_b32_e32 v128, 16, v182
	s_waitcnt lgkmcnt(0)
	v_and_b32_e32 v129, 0xffff0000, v182
	v_pk_fma_f32 v[114:115], v[114:115], 0.5, v[128:129] op_sel_hi:[1,0,1]
	v_lshlrev_b32_e32 v128, 16, v183
	v_and_b32_e32 v129, 0xffff0000, v183
	v_pk_fma_f32 v[116:117], v[116:117], 0.5, v[128:129] op_sel_hi:[1,0,1]
	v_cvt_pk_bf16_f32 v114, v114, v115
	v_cvt_pk_bf16_f32 v115, v116, v117
	v_lshlrev_b32_e32 v116, 16, v184
	v_and_b32_e32 v117, 0xffff0000, v184
	v_pk_fma_f32 v[106:107], v[106:107], 0.5, v[116:117] op_sel_hi:[1,0,1]
	s_mov_b64 s[18:19], 0x8000
	v_cvt_pk_bf16_f32 v116, v106, v107
	v_lshlrev_b32_e32 v106, 16, v185
	v_and_b32_e32 v107, 0xffff0000, v185
	v_pk_fma_f32 v[106:107], v[108:109], 0.5, v[106:107] op_sel_hi:[1,0,1]
	s_nop 0
	v_cvt_pk_bf16_f32 v117, v106, v107
	v_and_b32_e32 v107, 0xffff0000, v114
	v_lshlrev_b32_e32 v106, 16, v114
	v_mul_f32_e32 v108, v107, v107
	v_fmac_f32_e32 v108, v106, v106
	v_lshlrev_b32_e32 v106, 16, v115
	v_fmac_f32_e32 v108, v106, v106
	v_and_b32_e32 v106, 0xffff0000, v115
	v_fmac_f32_e32 v108, v106, v106
	v_lshlrev_b32_e32 v106, 16, v116
	v_fmac_f32_e32 v108, v106, v106
	v_and_b32_e32 v106, 0xffff0000, v116
	v_fmac_f32_e32 v108, v106, v106
	v_lshlrev_b32_e32 v106, 16, v117
	v_fmac_f32_e32 v108, v106, v106
	v_and_b32_e32 v106, 0xffff0000, v117
	v_fmac_f32_e32 v108, v106, v106
	v_lshlrev_b32_e32 v106, 16, v178
	v_and_b32_e32 v107, 0xffff0000, v178
	v_pk_fma_f32 v[102:103], v[102:103], 0.5, v[106:107] op_sel_hi:[1,0,1]
	v_lshlrev_b32_e32 v106, 16, v179
	v_and_b32_e32 v107, 0xffff0000, v179
	v_pk_fma_f32 v[104:105], v[104:105], 0.5, v[106:107] op_sel_hi:[1,0,1]
	v_cvt_pk_bf16_f32 v102, v102, v103
	v_cvt_pk_bf16_f32 v103, v104, v105
	v_lshlrev_b32_e32 v104, 16, v180
	v_and_b32_e32 v105, 0xffff0000, v180
	v_pk_fma_f32 v[98:99], v[98:99], 0.5, v[104:105] op_sel_hi:[1,0,1]
	s_nop 0
	v_cvt_pk_bf16_f32 v104, v98, v99
	v_lshlrev_b32_e32 v98, 16, v181
	v_and_b32_e32 v99, 0xffff0000, v181
	v_pk_fma_f32 v[98:99], v[100:101], 0.5, v[98:99] op_sel_hi:[1,0,1]
	v_lshl_add_u64 v[100:101], v[210:211], 0, s[18:19]
	v_cvt_pk_bf16_f32 v105, v98, v99
	v_and_b32_e32 v99, 0xffff0000, v102
	v_lshlrev_b32_e32 v98, 16, v102
	v_mul_f32_e32 v99, v99, v99
	v_fmac_f32_e32 v99, v98, v98
	v_lshlrev_b32_e32 v98, 16, v103
	v_fmac_f32_e32 v99, v98, v98
	v_and_b32_e32 v98, 0xffff0000, v103
	v_fmac_f32_e32 v99, v98, v98
	v_lshlrev_b32_e32 v98, 16, v104
	v_fmac_f32_e32 v99, v98, v98
	v_and_b32_e32 v98, 0xffff0000, v104
	v_fmac_f32_e32 v99, v98, v98
	v_lshlrev_b32_e32 v98, 16, v105
	v_fmac_f32_e32 v99, v98, v98
	v_and_b32_e32 v98, 0xffff0000, v105
	v_fmac_f32_e32 v99, v98, v98
	v_add_f32_e32 v98, v108, v99
	v_mov_b32_e32 v99, v98
	s_nop 1
	v_permlane16_swap_b32_e32 v99, v98
	s_mov_b64 s[18:19], 0x8100
	v_lshl_add_u64 v[106:107], v[210:211], 0, s[18:19]
	global_store_dwordx4 v[100:101], v[114:117], off
	global_store_dwordx4 v[106:107], v[102:105], off
	s_waitcnt lgkmcnt(0)
	v_add_f32_e32 v98, v98, v99
	v_mov_b32_e32 v99, v98
	s_nop 1
	v_permlane32_swap_b32_e32 v99, v98
	s_and_saveexec_b64 s[18:19], vcc
	s_cbranch_execz .LBB0_1270
	s_waitcnt lgkmcnt(0)
	v_add_f32_e32 v98, v98, v99
	v_mul_f32_e32 v98, 0x48800000, v98
	v_cvt_u32_f32_e32 v98, v98
	v_mov_b32_e32 v99, v0
	global_atomic_add_x2 v[126:127], v[98:99], off offset:128
.LBB0_1270:
	s_or_b64 exec, exec, s[18:19]
	v_lshlrev_b32_e32 v98, 16, v174
	s_waitcnt lgkmcnt(0)
	v_and_b32_e32 v99, 0xffff0000, v174
	v_pk_fma_f32 v[94:95], v[94:95], 0.5, v[98:99] op_sel_hi:[1,0,1]
	v_lshlrev_b32_e32 v98, 16, v175
	v_and_b32_e32 v99, 0xffff0000, v175
	v_pk_fma_f32 v[96:97], v[96:97], 0.5, v[98:99] op_sel_hi:[1,0,1]
	v_cvt_pk_bf16_f32 v94, v94, v95
	v_cvt_pk_bf16_f32 v95, v96, v97
	v_lshlrev_b32_e32 v96, 16, v176
	v_and_b32_e32 v97, 0xffff0000, v176
	v_pk_fma_f32 v[90:91], v[90:91], 0.5, v[96:97] op_sel_hi:[1,0,1]
	s_mov_b64 s[18:19], 0x10100
	v_cvt_pk_bf16_f32 v96, v90, v91
	v_lshlrev_b32_e32 v90, 16, v177
	v_and_b32_e32 v91, 0xffff0000, v177
	v_pk_fma_f32 v[90:91], v[92:93], 0.5, v[90:91] op_sel_hi:[1,0,1]
	s_nop 0
	v_cvt_pk_bf16_f32 v97, v90, v91
	v_and_b32_e32 v91, 0xffff0000, v94
	v_lshlrev_b32_e32 v90, 16, v94
	v_mul_f32_e32 v92, v91, v91
	v_fmac_f32_e32 v92, v90, v90
	v_lshlrev_b32_e32 v90, 16, v95
	v_fmac_f32_e32 v92, v90, v90
	v_and_b32_e32 v90, 0xffff0000, v95
	v_fmac_f32_e32 v92, v90, v90
	v_lshlrev_b32_e32 v90, 16, v96
	v_fmac_f32_e32 v92, v90, v90
	v_and_b32_e32 v90, 0xffff0000, v96
	v_fmac_f32_e32 v92, v90, v90
	v_lshlrev_b32_e32 v90, 16, v97
	v_fmac_f32_e32 v92, v90, v90
	v_and_b32_e32 v90, 0xffff0000, v97
	v_fmac_f32_e32 v92, v90, v90
	v_lshlrev_b32_e32 v90, 16, v170
	v_and_b32_e32 v91, 0xffff0000, v170
	v_pk_fma_f32 v[86:87], v[86:87], 0.5, v[90:91] op_sel_hi:[1,0,1]
	v_lshlrev_b32_e32 v90, 16, v171
	v_and_b32_e32 v91, 0xffff0000, v171
	v_pk_fma_f32 v[88:89], v[88:89], 0.5, v[90:91] op_sel_hi:[1,0,1]
	v_cvt_pk_bf16_f32 v86, v86, v87
	v_cvt_pk_bf16_f32 v87, v88, v89
	v_lshlrev_b32_e32 v88, 16, v172
	v_and_b32_e32 v89, 0xffff0000, v172
	v_pk_fma_f32 v[82:83], v[82:83], 0.5, v[88:89] op_sel_hi:[1,0,1]
	v_lshl_add_u64 v[90:91], v[210:211], 0, s[18:19]
	v_cvt_pk_bf16_f32 v88, v82, v83
	v_lshlrev_b32_e32 v82, 16, v173
	v_and_b32_e32 v83, 0xffff0000, v173
	v_pk_fma_f32 v[82:83], v[84:85], 0.5, v[82:83] op_sel_hi:[1,0,1]
	v_lshl_add_u64 v[84:85], v[210:211], 0, s[90:91]
	v_cvt_pk_bf16_f32 v89, v82, v83
	v_and_b32_e32 v83, 0xffff0000, v86
	v_lshlrev_b32_e32 v82, 16, v86
	v_mul_f32_e32 v83, v83, v83
	v_fmac_f32_e32 v83, v82, v82
	v_lshlrev_b32_e32 v82, 16, v87
	v_fmac_f32_e32 v83, v82, v82
	v_and_b32_e32 v82, 0xffff0000, v87
	v_fmac_f32_e32 v83, v82, v82
	v_lshlrev_b32_e32 v82, 16, v88
	v_fmac_f32_e32 v83, v82, v82
	v_and_b32_e32 v82, 0xffff0000, v88
	v_fmac_f32_e32 v83, v82, v82
	v_lshlrev_b32_e32 v82, 16, v89
	v_fmac_f32_e32 v83, v82, v82
	v_and_b32_e32 v82, 0xffff0000, v89
	v_fmac_f32_e32 v83, v82, v82
	v_add_f32_e32 v82, v92, v83
	v_mov_b32_e32 v83, v82
	s_nop 1
	v_permlane16_swap_b32_e32 v83, v82
	global_store_dwordx4 v[84:85], v[94:97], off
	global_store_dwordx4 v[90:91], v[86:89], off
	s_waitcnt lgkmcnt(0)
	v_add_f32_e32 v82, v82, v83
	v_mov_b32_e32 v83, v82
	s_nop 1
	v_permlane32_swap_b32_e32 v83, v82
	s_and_saveexec_b64 s[18:19], vcc
	s_cbranch_execz .LBB0_1272
	s_waitcnt lgkmcnt(0)
	v_add_f32_e32 v82, v82, v83
	v_mul_f32_e32 v82, 0x48800000, v82
	v_cvt_u32_f32_e32 v82, v82
	v_mov_b32_e32 v83, v0
	global_atomic_add_x2 v[126:127], v[82:83], off offset:256
.LBB0_1272:
	s_or_b64 exec, exec, s[18:19]
	v_lshlrev_b32_e32 v82, 16, v166
	s_waitcnt lgkmcnt(0)
	v_and_b32_e32 v83, 0xffff0000, v166
	v_pk_fma_f32 v[78:79], v[78:79], 0.5, v[82:83] op_sel_hi:[1,0,1]
	v_lshlrev_b32_e32 v82, 16, v167
	v_and_b32_e32 v83, 0xffff0000, v167
	v_pk_fma_f32 v[80:81], v[80:81], 0.5, v[82:83] op_sel_hi:[1,0,1]
	v_cvt_pk_bf16_f32 v78, v78, v79
	v_cvt_pk_bf16_f32 v79, v80, v81
	v_lshlrev_b32_e32 v80, 16, v168
	v_and_b32_e32 v81, 0xffff0000, v168
	v_pk_fma_f32 v[74:75], v[74:75], 0.5, v[80:81] op_sel_hi:[1,0,1]
	s_mov_b64 s[18:19], 0x18000
	v_cvt_pk_bf16_f32 v80, v74, v75
	v_lshlrev_b32_e32 v74, 16, v169
	v_and_b32_e32 v75, 0xffff0000, v169
	v_pk_fma_f32 v[74:75], v[76:77], 0.5, v[74:75] op_sel_hi:[1,0,1]
	s_nop 0
	v_cvt_pk_bf16_f32 v81, v74, v75
	v_and_b32_e32 v75, 0xffff0000, v78
	v_lshlrev_b32_e32 v74, 16, v78
	v_mul_f32_e32 v76, v75, v75
	v_fmac_f32_e32 v76, v74, v74
	v_lshlrev_b32_e32 v74, 16, v79
	v_fmac_f32_e32 v76, v74, v74
	v_and_b32_e32 v74, 0xffff0000, v79
	v_fmac_f32_e32 v76, v74, v74
	v_lshlrev_b32_e32 v74, 16, v80
	v_fmac_f32_e32 v76, v74, v74
	v_and_b32_e32 v74, 0xffff0000, v80
	v_fmac_f32_e32 v76, v74, v74
	v_lshlrev_b32_e32 v74, 16, v81
	v_fmac_f32_e32 v76, v74, v74
	v_and_b32_e32 v74, 0xffff0000, v81
	v_fmac_f32_e32 v76, v74, v74
	v_lshlrev_b32_e32 v74, 16, v162
	v_and_b32_e32 v75, 0xffff0000, v162
	v_pk_fma_f32 v[70:71], v[70:71], 0.5, v[74:75] op_sel_hi:[1,0,1]
	v_lshlrev_b32_e32 v74, 16, v163
	v_and_b32_e32 v75, 0xffff0000, v163
	v_pk_fma_f32 v[72:73], v[72:73], 0.5, v[74:75] op_sel_hi:[1,0,1]
	v_cvt_pk_bf16_f32 v70, v70, v71
	v_cvt_pk_bf16_f32 v71, v72, v73
	v_lshlrev_b32_e32 v72, 16, v164
	v_and_b32_e32 v73, 0xffff0000, v164
	v_pk_fma_f32 v[66:67], v[66:67], 0.5, v[72:73] op_sel_hi:[1,0,1]
	s_nop 0
	v_cvt_pk_bf16_f32 v72, v66, v67
	v_lshlrev_b32_e32 v66, 16, v165
	v_and_b32_e32 v67, 0xffff0000, v165
	v_pk_fma_f32 v[66:67], v[68:69], 0.5, v[66:67] op_sel_hi:[1,0,1]
	v_lshl_add_u64 v[68:69], v[210:211], 0, s[18:19]
	v_cvt_pk_bf16_f32 v73, v66, v67
	v_and_b32_e32 v67, 0xffff0000, v70
	v_lshlrev_b32_e32 v66, 16, v70
	v_mul_f32_e32 v67, v67, v67
	v_fmac_f32_e32 v67, v66, v66
	v_lshlrev_b32_e32 v66, 16, v71
	v_fmac_f32_e32 v67, v66, v66
	v_and_b32_e32 v66, 0xffff0000, v71
	v_fmac_f32_e32 v67, v66, v66
	v_lshlrev_b32_e32 v66, 16, v72
	v_fmac_f32_e32 v67, v66, v66
	v_and_b32_e32 v66, 0xffff0000, v72
	v_fmac_f32_e32 v67, v66, v66
	v_lshlrev_b32_e32 v66, 16, v73
	v_fmac_f32_e32 v67, v66, v66
	v_and_b32_e32 v66, 0xffff0000, v73
	v_fmac_f32_e32 v67, v66, v66
	v_add_f32_e32 v66, v76, v67
	v_mov_b32_e32 v67, v66
	s_nop 1
	v_permlane16_swap_b32_e32 v67, v66
	s_mov_b64 s[18:19], 0x18100
	v_lshl_add_u64 v[74:75], v[210:211], 0, s[18:19]
	global_store_dwordx4 v[68:69], v[78:81], off
	global_store_dwordx4 v[74:75], v[70:73], off
	s_waitcnt lgkmcnt(0)
	v_add_f32_e32 v66, v66, v67
	v_mov_b32_e32 v67, v66
	s_nop 1
	v_permlane32_swap_b32_e32 v67, v66
	s_and_saveexec_b64 s[18:19], vcc
	s_cbranch_execz .LBB0_1274
	s_waitcnt lgkmcnt(0)
	v_add_f32_e32 v66, v66, v67
	v_mul_f32_e32 v66, 0x48800000, v66
	v_cvt_u32_f32_e32 v66, v66
	v_mov_b32_e32 v67, v0
	global_atomic_add_x2 v[126:127], v[66:67], off offset:384
.LBB0_1274:
	s_or_b64 exec, exec, s[18:19]
	v_lshlrev_b32_e32 v66, 16, v154
	s_waitcnt lgkmcnt(0)
	v_and_b32_e32 v67, 0xffff0000, v154
	v_pk_fma_f32 v[62:63], v[62:63], 0.5, v[66:67] op_sel_hi:[1,0,1]
	v_lshlrev_b32_e32 v66, 16, v155
	v_and_b32_e32 v67, 0xffff0000, v155
	v_pk_fma_f32 v[64:65], v[64:65], 0.5, v[66:67] op_sel_hi:[1,0,1]
	v_cvt_pk_bf16_f32 v62, v62, v63
	v_cvt_pk_bf16_f32 v63, v64, v65
	v_lshlrev_b32_e32 v64, 16, v156
	v_and_b32_e32 v65, 0xffff0000, v156
	v_pk_fma_f32 v[58:59], v[58:59], 0.5, v[64:65] op_sel_hi:[1,0,1]
	s_mov_b64 s[18:19], 0x40100
	v_cvt_pk_bf16_f32 v64, v58, v59
	v_lshlrev_b32_e32 v58, 16, v157
	v_and_b32_e32 v59, 0xffff0000, v157
	v_pk_fma_f32 v[58:59], v[60:61], 0.5, v[58:59] op_sel_hi:[1,0,1]
	s_nop 0
	v_cvt_pk_bf16_f32 v65, v58, v59
	v_and_b32_e32 v59, 0xffff0000, v62
	v_lshlrev_b32_e32 v58, 16, v62
	v_mul_f32_e32 v60, v59, v59
	v_fmac_f32_e32 v60, v58, v58
	v_lshlrev_b32_e32 v58, 16, v63
	v_fmac_f32_e32 v60, v58, v58
	v_and_b32_e32 v58, 0xffff0000, v63
	v_fmac_f32_e32 v60, v58, v58
	v_lshlrev_b32_e32 v58, 16, v64
	v_fmac_f32_e32 v60, v58, v58
	v_and_b32_e32 v58, 0xffff0000, v64
	v_fmac_f32_e32 v60, v58, v58
	v_lshlrev_b32_e32 v58, 16, v65
	v_fmac_f32_e32 v60, v58, v58
	v_and_b32_e32 v58, 0xffff0000, v65
	v_fmac_f32_e32 v60, v58, v58
	v_lshlrev_b32_e32 v58, 16, v146
	v_and_b32_e32 v59, 0xffff0000, v146
	v_pk_fma_f32 v[54:55], v[54:55], 0.5, v[58:59] op_sel_hi:[1,0,1]
	v_lshlrev_b32_e32 v58, 16, v147
	v_and_b32_e32 v59, 0xffff0000, v147
	v_pk_fma_f32 v[56:57], v[56:57], 0.5, v[58:59] op_sel_hi:[1,0,1]
	v_cvt_pk_bf16_f32 v54, v54, v55
	v_cvt_pk_bf16_f32 v55, v56, v57
	v_lshlrev_b32_e32 v56, 16, v148
	v_and_b32_e32 v57, 0xffff0000, v148
	v_pk_fma_f32 v[50:51], v[50:51], 0.5, v[56:57] op_sel_hi:[1,0,1]
	v_lshl_add_u64 v[58:59], v[210:211], 0, s[18:19]
	v_cvt_pk_bf16_f32 v56, v50, v51
	v_lshlrev_b32_e32 v50, 16, v149
	v_and_b32_e32 v51, 0xffff0000, v149
	v_pk_fma_f32 v[50:51], v[52:53], 0.5, v[50:51] op_sel_hi:[1,0,1]
	v_lshl_add_u64 v[52:53], v[210:211], 0, s[72:73]
	v_cvt_pk_bf16_f32 v57, v50, v51
	v_and_b32_e32 v51, 0xffff0000, v54
	v_lshlrev_b32_e32 v50, 16, v54
	v_mul_f32_e32 v51, v51, v51
	v_fmac_f32_e32 v51, v50, v50
	v_lshlrev_b32_e32 v50, 16, v55
	v_fmac_f32_e32 v51, v50, v50
	v_and_b32_e32 v50, 0xffff0000, v55
	v_fmac_f32_e32 v51, v50, v50
	v_lshlrev_b32_e32 v50, 16, v56
	v_fmac_f32_e32 v51, v50, v50
	v_and_b32_e32 v50, 0xffff0000, v56
	v_fmac_f32_e32 v51, v50, v50
	v_lshlrev_b32_e32 v50, 16, v57
	v_fmac_f32_e32 v51, v50, v50
	v_and_b32_e32 v50, 0xffff0000, v57
	v_fmac_f32_e32 v51, v50, v50
	v_add_f32_e32 v50, v60, v51
	v_mov_b32_e32 v51, v50
	s_nop 1
	v_permlane16_swap_b32_e32 v51, v50
	global_store_dwordx4 v[52:53], v[62:65], off
	global_store_dwordx4 v[58:59], v[54:57], off
	s_waitcnt lgkmcnt(0)
	v_add_f32_e32 v50, v50, v51
	v_mov_b32_e32 v51, v50
	s_nop 1
	v_permlane32_swap_b32_e32 v51, v50
	s_and_saveexec_b64 s[18:19], vcc
	s_cbranch_execz .LBB0_1276
	s_waitcnt lgkmcnt(0)
	v_add_f32_e32 v50, v50, v51
	v_mul_f32_e32 v50, 0x48800000, v50
	v_cvt_u32_f32_e32 v50, v50
	v_mov_b32_e32 v51, v0
	global_atomic_add_x2 v[126:127], v[50:51], off offset:1024
.LBB0_1276:
	s_or_b64 exec, exec, s[18:19]
	v_lshlrev_b32_e32 v50, 16, v142
	s_waitcnt lgkmcnt(0)
	v_and_b32_e32 v51, 0xffff0000, v142
	v_pk_fma_f32 v[46:47], v[46:47], 0.5, v[50:51] op_sel_hi:[1,0,1]
	v_lshlrev_b32_e32 v50, 16, v143
	v_and_b32_e32 v51, 0xffff0000, v143
	v_pk_fma_f32 v[48:49], v[48:49], 0.5, v[50:51] op_sel_hi:[1,0,1]
	v_cvt_pk_bf16_f32 v46, v46, v47
	v_cvt_pk_bf16_f32 v47, v48, v49
	v_lshlrev_b32_e32 v48, 16, v144
	v_and_b32_e32 v49, 0xffff0000, v144
	v_pk_fma_f32 v[42:43], v[42:43], 0.5, v[48:49] op_sel_hi:[1,0,1]
	s_mov_b64 s[18:19], 0x48000
	v_cvt_pk_bf16_f32 v48, v42, v43
	v_lshlrev_b32_e32 v42, 16, v145
	v_and_b32_e32 v43, 0xffff0000, v145
	v_pk_fma_f32 v[42:43], v[44:45], 0.5, v[42:43] op_sel_hi:[1,0,1]
	s_nop 0
	v_cvt_pk_bf16_f32 v49, v42, v43
	v_and_b32_e32 v43, 0xffff0000, v46
	v_lshlrev_b32_e32 v42, 16, v46
	v_mul_f32_e32 v44, v43, v43
	v_fmac_f32_e32 v44, v42, v42
	v_lshlrev_b32_e32 v42, 16, v47
	v_fmac_f32_e32 v44, v42, v42
	v_and_b32_e32 v42, 0xffff0000, v47
	v_fmac_f32_e32 v44, v42, v42
	v_lshlrev_b32_e32 v42, 16, v48
	v_fmac_f32_e32 v44, v42, v42
	v_and_b32_e32 v42, 0xffff0000, v48
	v_fmac_f32_e32 v44, v42, v42
	v_lshlrev_b32_e32 v42, 16, v49
	v_fmac_f32_e32 v44, v42, v42
	v_and_b32_e32 v42, 0xffff0000, v49
	v_fmac_f32_e32 v44, v42, v42
	v_lshlrev_b32_e32 v42, 16, v138
	v_and_b32_e32 v43, 0xffff0000, v138
	v_pk_fma_f32 v[38:39], v[38:39], 0.5, v[42:43] op_sel_hi:[1,0,1]
	v_lshlrev_b32_e32 v42, 16, v139
	v_and_b32_e32 v43, 0xffff0000, v139
	v_pk_fma_f32 v[40:41], v[40:41], 0.5, v[42:43] op_sel_hi:[1,0,1]
	v_cvt_pk_bf16_f32 v38, v38, v39
	v_cvt_pk_bf16_f32 v39, v40, v41
	v_lshlrev_b32_e32 v40, 16, v140
	v_and_b32_e32 v41, 0xffff0000, v140
	v_pk_fma_f32 v[34:35], v[34:35], 0.5, v[40:41] op_sel_hi:[1,0,1]
	s_nop 0
	v_cvt_pk_bf16_f32 v40, v34, v35
	v_lshlrev_b32_e32 v34, 16, v141
	v_and_b32_e32 v35, 0xffff0000, v141
	v_pk_fma_f32 v[34:35], v[36:37], 0.5, v[34:35] op_sel_hi:[1,0,1]
	v_lshl_add_u64 v[36:37], v[210:211], 0, s[18:19]
	v_cvt_pk_bf16_f32 v41, v34, v35
	v_and_b32_e32 v35, 0xffff0000, v38
	v_lshlrev_b32_e32 v34, 16, v38
	v_mul_f32_e32 v35, v35, v35
	v_fmac_f32_e32 v35, v34, v34
	v_lshlrev_b32_e32 v34, 16, v39
	v_fmac_f32_e32 v35, v34, v34
	v_and_b32_e32 v34, 0xffff0000, v39
	v_fmac_f32_e32 v35, v34, v34
	v_lshlrev_b32_e32 v34, 16, v40
	v_fmac_f32_e32 v35, v34, v34
	v_and_b32_e32 v34, 0xffff0000, v40
	v_fmac_f32_e32 v35, v34, v34
	v_lshlrev_b32_e32 v34, 16, v41
	v_fmac_f32_e32 v35, v34, v34
	v_and_b32_e32 v34, 0xffff0000, v41
	v_fmac_f32_e32 v35, v34, v34
	v_add_f32_e32 v34, v44, v35
	v_mov_b32_e32 v35, v34
	s_nop 1
	v_permlane16_swap_b32_e32 v35, v34
	s_mov_b64 s[18:19], 0x48100
	v_lshl_add_u64 v[42:43], v[210:211], 0, s[18:19]
	global_store_dwordx4 v[36:37], v[46:49], off
	global_store_dwordx4 v[42:43], v[38:41], off
	s_waitcnt lgkmcnt(0)
	v_add_f32_e32 v34, v34, v35
	v_mov_b32_e32 v35, v34
	s_nop 1
	v_permlane32_swap_b32_e32 v35, v34
	s_and_saveexec_b64 s[18:19], vcc
	s_cbranch_execz .LBB0_1278
	s_waitcnt lgkmcnt(0)
	v_add_f32_e32 v34, v34, v35
	v_mul_f32_e32 v34, 0x48800000, v34
	v_cvt_u32_f32_e32 v34, v34
	v_mov_b32_e32 v35, v0
	global_atomic_add_x2 v[126:127], v[34:35], off offset:1152
.LBB0_1278:
	s_or_b64 exec, exec, s[18:19]
	s_waitcnt vmcnt(15)
	v_lshlrev_b32_e32 v34, 16, v134
	s_waitcnt lgkmcnt(0)
	v_and_b32_e32 v35, 0xffff0000, v134
	v_pk_fma_f32 v[30:31], v[30:31], 0.5, v[34:35] op_sel_hi:[1,0,1]
	v_lshlrev_b32_e32 v34, 16, v135
	v_and_b32_e32 v35, 0xffff0000, v135
	v_pk_fma_f32 v[32:33], v[32:33], 0.5, v[34:35] op_sel_hi:[1,0,1]
	v_cvt_pk_bf16_f32 v30, v30, v31
	v_cvt_pk_bf16_f32 v31, v32, v33
	v_lshlrev_b32_e32 v32, 16, v136
	v_and_b32_e32 v33, 0xffff0000, v136
	v_pk_fma_f32 v[26:27], v[26:27], 0.5, v[32:33] op_sel_hi:[1,0,1]
	s_mov_b64 s[18:19], 0x50000
	v_cvt_pk_bf16_f32 v32, v26, v27
	v_lshlrev_b32_e32 v26, 16, v137
	v_and_b32_e32 v27, 0xffff0000, v137
	v_pk_fma_f32 v[26:27], v[28:29], 0.5, v[26:27] op_sel_hi:[1,0,1]
	s_nop 0
	v_cvt_pk_bf16_f32 v33, v26, v27
	v_and_b32_e32 v27, 0xffff0000, v30
	v_lshlrev_b32_e32 v26, 16, v30
	v_mul_f32_e32 v28, v27, v27
	v_fmac_f32_e32 v28, v26, v26
	v_lshlrev_b32_e32 v26, 16, v31
	v_fmac_f32_e32 v28, v26, v26
	v_and_b32_e32 v26, 0xffff0000, v31
	v_fmac_f32_e32 v28, v26, v26
	v_lshlrev_b32_e32 v26, 16, v32
	v_fmac_f32_e32 v28, v26, v26
	v_and_b32_e32 v26, 0xffff0000, v32
	v_fmac_f32_e32 v28, v26, v26
	v_lshlrev_b32_e32 v26, 16, v33
	v_fmac_f32_e32 v28, v26, v26
	v_and_b32_e32 v26, 0xffff0000, v33
	v_fmac_f32_e32 v28, v26, v26
	s_waitcnt vmcnt(14)
	v_lshlrev_b32_e32 v26, 16, v122
	v_and_b32_e32 v27, 0xffff0000, v122
	v_pk_fma_f32 v[22:23], v[22:23], 0.5, v[26:27] op_sel_hi:[1,0,1]
	v_lshlrev_b32_e32 v26, 16, v123
	v_and_b32_e32 v27, 0xffff0000, v123
	v_pk_fma_f32 v[24:25], v[24:25], 0.5, v[26:27] op_sel_hi:[1,0,1]
	v_cvt_pk_bf16_f32 v22, v22, v23
	v_cvt_pk_bf16_f32 v23, v24, v25
	v_lshlrev_b32_e32 v24, 16, v124
	v_and_b32_e32 v25, 0xffff0000, v124
	v_pk_fma_f32 v[18:19], v[18:19], 0.5, v[24:25] op_sel_hi:[1,0,1]
	s_nop 0
	v_cvt_pk_bf16_f32 v24, v18, v19
	v_lshlrev_b32_e32 v18, 16, v125
	v_and_b32_e32 v19, 0xffff0000, v125
	v_pk_fma_f32 v[18:19], v[20:21], 0.5, v[18:19] op_sel_hi:[1,0,1]
	v_lshl_add_u64 v[20:21], v[210:211], 0, s[18:19]
	v_cvt_pk_bf16_f32 v25, v18, v19
	v_and_b32_e32 v19, 0xffff0000, v22
	v_lshlrev_b32_e32 v18, 16, v22
	v_mul_f32_e32 v19, v19, v19
	v_fmac_f32_e32 v19, v18, v18
	v_lshlrev_b32_e32 v18, 16, v23
	v_fmac_f32_e32 v19, v18, v18
	v_and_b32_e32 v18, 0xffff0000, v23
	v_fmac_f32_e32 v19, v18, v18
	v_lshlrev_b32_e32 v18, 16, v24
	v_fmac_f32_e32 v19, v18, v18
	v_and_b32_e32 v18, 0xffff0000, v24
	v_fmac_f32_e32 v19, v18, v18
	v_lshlrev_b32_e32 v18, 16, v25
	v_fmac_f32_e32 v19, v18, v18
	v_and_b32_e32 v18, 0xffff0000, v25
	v_fmac_f32_e32 v19, v18, v18
	v_add_f32_e32 v18, v28, v19
	v_mov_b32_e32 v19, v18
	s_nop 1
	v_permlane16_swap_b32_e32 v19, v18
	s_mov_b64 s[18:19], 0x50100
	v_lshl_add_u64 v[26:27], v[210:211], 0, s[18:19]
	global_store_dwordx4 v[20:21], v[30:33], off
	global_store_dwordx4 v[26:27], v[22:25], off
	s_waitcnt lgkmcnt(0)
	v_add_f32_e32 v18, v18, v19
	v_mov_b32_e32 v19, v18
	s_nop 1
	v_permlane32_swap_b32_e32 v19, v18
	s_and_saveexec_b64 s[18:19], vcc
	s_cbranch_execz .LBB0_1280
	s_waitcnt lgkmcnt(0)
	v_add_f32_e32 v18, v18, v19
	v_mul_f32_e32 v18, 0x48800000, v18
	v_cvt_u32_f32_e32 v18, v18
	v_mov_b32_e32 v19, v0
	global_atomic_add_x2 v[126:127], v[18:19], off offset:1280
.LBB0_1280:
	s_or_b64 exec, exec, s[18:19]
	s_waitcnt vmcnt(15)
	v_lshlrev_b32_e32 v18, 16, v118
	s_waitcnt lgkmcnt(0)
	v_and_b32_e32 v19, 0xffff0000, v118
	v_pk_fma_f32 v[14:15], v[14:15], 0.5, v[18:19] op_sel_hi:[1,0,1]
	v_lshlrev_b32_e32 v18, 16, v119
	v_and_b32_e32 v19, 0xffff0000, v119
	v_pk_fma_f32 v[16:17], v[16:17], 0.5, v[18:19] op_sel_hi:[1,0,1]
	v_cvt_pk_bf16_f32 v14, v14, v15
	v_cvt_pk_bf16_f32 v15, v16, v17
	v_lshlrev_b32_e32 v16, 16, v120
	v_and_b32_e32 v17, 0xffff0000, v120
	v_pk_fma_f32 v[10:11], v[10:11], 0.5, v[16:17] op_sel_hi:[1,0,1]
	s_mov_b64 s[18:19], 0x58000
	v_cvt_pk_bf16_f32 v16, v10, v11
	v_lshlrev_b32_e32 v10, 16, v121
	v_and_b32_e32 v11, 0xffff0000, v121
	v_pk_fma_f32 v[10:11], v[12:13], 0.5, v[10:11] op_sel_hi:[1,0,1]
	s_nop 0
	v_cvt_pk_bf16_f32 v17, v10, v11
	v_and_b32_e32 v11, 0xffff0000, v14
	v_lshlrev_b32_e32 v10, 16, v14
	v_mul_f32_e32 v12, v11, v11
	v_fmac_f32_e32 v12, v10, v10
	v_lshlrev_b32_e32 v10, 16, v15
	v_fmac_f32_e32 v12, v10, v10
	v_and_b32_e32 v10, 0xffff0000, v15
	v_fmac_f32_e32 v12, v10, v10
	v_lshlrev_b32_e32 v10, 16, v16
	v_fmac_f32_e32 v12, v10, v10
	v_and_b32_e32 v10, 0xffff0000, v16
	v_fmac_f32_e32 v12, v10, v10
	v_lshlrev_b32_e32 v10, 16, v17
	v_fmac_f32_e32 v12, v10, v10
	v_and_b32_e32 v10, 0xffff0000, v17
	v_fmac_f32_e32 v12, v10, v10
	s_waitcnt vmcnt(14)
	v_lshlrev_b32_e32 v10, 16, v110
	v_and_b32_e32 v11, 0xffff0000, v110
	v_pk_fma_f32 v[6:7], v[6:7], 0.5, v[10:11] op_sel_hi:[1,0,1]
	v_lshlrev_b32_e32 v10, 16, v111
	v_and_b32_e32 v11, 0xffff0000, v111
	v_pk_fma_f32 v[8:9], v[8:9], 0.5, v[10:11] op_sel_hi:[1,0,1]
	v_cvt_pk_bf16_f32 v6, v6, v7
	v_cvt_pk_bf16_f32 v7, v8, v9
	v_lshlrev_b32_e32 v8, 16, v112
	v_and_b32_e32 v9, 0xffff0000, v112
	v_pk_fma_f32 v[2:3], v[2:3], 0.5, v[8:9] op_sel_hi:[1,0,1]
	s_nop 0
	v_cvt_pk_bf16_f32 v8, v2, v3
	v_lshlrev_b32_e32 v2, 16, v113
	v_and_b32_e32 v3, 0xffff0000, v113
	v_pk_fma_f32 v[2:3], v[4:5], 0.5, v[2:3] op_sel_hi:[1,0,1]
	v_lshl_add_u64 v[4:5], v[210:211], 0, s[18:19]
	v_cvt_pk_bf16_f32 v9, v2, v3
	v_and_b32_e32 v3, 0xffff0000, v6
	v_lshlrev_b32_e32 v2, 16, v6
	v_mul_f32_e32 v3, v3, v3
	v_fmac_f32_e32 v3, v2, v2
	v_lshlrev_b32_e32 v2, 16, v7
	v_fmac_f32_e32 v3, v2, v2
	v_and_b32_e32 v2, 0xffff0000, v7
	v_fmac_f32_e32 v3, v2, v2
	v_lshlrev_b32_e32 v2, 16, v8
	v_fmac_f32_e32 v3, v2, v2
	v_and_b32_e32 v2, 0xffff0000, v8
	v_fmac_f32_e32 v3, v2, v2
	v_lshlrev_b32_e32 v2, 16, v9
	v_fmac_f32_e32 v3, v2, v2
	v_and_b32_e32 v2, 0xffff0000, v9
	v_fmac_f32_e32 v3, v2, v2
	v_add_f32_e32 v2, v12, v3
	v_mov_b32_e32 v3, v2
	s_nop 1
	v_permlane16_swap_b32_e32 v3, v2
	s_mov_b64 s[18:19], 0x58100
	v_lshl_add_u64 v[10:11], v[210:211], 0, s[18:19]
	global_store_dwordx4 v[4:5], v[14:17], off
	global_store_dwordx4 v[10:11], v[6:9], off
	s_waitcnt lgkmcnt(0)
	v_add_f32_e32 v2, v2, v3
	v_mov_b32_e32 v3, v2
	s_nop 1
	v_permlane32_swap_b32_e32 v3, v2
	s_and_saveexec_b64 s[18:19], vcc
	s_cbranch_execz .LBB0_1282
	s_waitcnt lgkmcnt(0)
	v_add_f32_e32 v2, v2, v3
	v_mul_f32_e32 v2, 0x48800000, v2
	v_cvt_u32_f32_e32 v2, v2
	v_mov_b32_e32 v3, v0
	global_atomic_add_x2 v[126:127], v[2:3], off offset:1408
